# S5 scan: abar^16/abar^256 loads issued with the other constants before pass 1; carry phase waits vmcnt(4) so the z-gate loads stay in flight across it
# speedup vs baseline: 1.0040x; 1.0040x over previous
; #define LAS __attribute__((address_space(3)))
; __device__ __forceinline__ bf16x8 pack8(f32x4 lo, f32x4 hi) { v4u w; w.x = pk2(lo[0], lo[1]); w.y = pk2(lo[2], lo[3]); w.z = pk2(hi[0], hi[1]); w.w = pk2(hi[2], hi[3]); return __builtin_bit_cast(bf16x8, w); }
; __device__ __forceinline__ void gmlp_compute(GmlpRegs& R, const Args& a, const Ctx& C, int c, int hd) {
;     ...
;     for (int ks = 0; ks < 4; ++ks) { f32x4 lo, hi;
; #pragma unroll
;         for (int e = 0; e < 8; ++e) { const int sl = 32 * ks + 8 * q + e;
;             const float v = __uint_as_float((unsigned)*(const LAS unsigned short*)(VL + sl * 260 + (16 * w + fr) * 2) << 16);
;             const float x = (v - ST[2 * sl]) * ST[2 * sl + 1] * lg + lb; if (e < 4) lo[e] = x; else hi[e - 4] = x; }
;         af[ks] = pack8(lo, hi); }
.LBB0_973:
	s_or_b64 exec, exec, s[4:5]
	s_waitcnt lgkmcnt(0)
	s_barrier
	v_add_u32_e32 v18, v165, v184
	ds_read_b128 v[2:5], v183
	ds_read_u16 v6, v18 offset:34816
	ds_read_u16 v7, v18 offset:35076
	ds_read_u16 v14, v18 offset:35596
	ds_read_u16 v15, v18 offset:36116
	ds_read_u16 v19, v18 offset:36636
	ds_read_u16 v20, v18 offset:43396
	ds_read_u16 v21, v18 offset:43916
	ds_read_u16 v22, v18 offset:44436
	s_waitcnt lgkmcnt(6)
	v_lshlrev_b32_e32 v11, 16, v7
	v_lshlrev_b32_e32 v10, 16, v6
	ds_read_b128 v[6:9], v168
	v_mov_b32_e32 v12, v2
	v_mov_b32_e32 v13, v4
	v_pk_add_f32 v[10:11], v[10:11], v[12:13] neg_lo:[0,1] neg_hi:[0,1]
	v_mov_b32_e32 v4, v3
	v_pk_mul_f32 v[2:3], v[4:5], v[10:11]
	s_waitcnt lgkmcnt(0)
	v_mov_b32_e32 v5, v8
	v_pk_fma_f32 v[10:11], v[98:99], v[2:3], v[100:101]
	v_add_u32_e32 v2, v165, v167
	v_lshlrev_b32_e32 v3, 16, v14
	ds_read_u16 v4, v2 offset:34816
	ds_read_u16 v14, v2 offset:35336
	ds_read_u16 v23, v2 offset:35856
	ds_read_u16 v24, v2 offset:42616
	ds_read_u16 v25, v2 offset:43136
	ds_read_u16 v113, v18 offset:61596
	s_waitcnt lgkmcnt(5)
	v_lshlrev_b32_e32 v2, 16, v4
	v_mov_b32_e32 v4, v6
	v_pk_add_f32 v[2:3], v[2:3], v[4:5] neg_lo:[0,1] neg_hi:[0,1]
	v_mov_b32_e32 v8, v7
	v_pk_mul_f32 v[6:7], v[8:9], v[2:3]
	ds_read_b128 v[2:5], v163
	v_pk_fma_f32 v[12:13], v[98:99], v[6:7], v[100:101]
	ds_read_b128 v[6:9], v166
	v_lshlrev_b32_e32 v15, 16, v15
	s_waitcnt lgkmcnt(6)
	v_lshlrev_b32_e32 v14, 16, v14
	s_waitcnt lgkmcnt(1)
	v_mov_b32_e32 v16, v2
	v_mov_b32_e32 v17, v4
	v_pk_add_f32 v[14:15], v[14:15], v[16:17] neg_lo:[0,1] neg_hi:[0,1]
	v_mov_b32_e32 v4, v3
	v_pk_mul_f32 v[2:3], v[4:5], v[14:15]
	s_waitcnt lgkmcnt(0)
	v_mov_b32_e32 v14, v6
	v_pk_fma_f32 v[4:5], v[98:99], v[2:3], v[100:101]
	v_lshlrev_b32_e32 v3, 16, v19
	v_lshlrev_b32_e32 v2, 16, v23
	v_mov_b32_e32 v15, v8
	v_pk_add_f32 v[2:3], v[2:3], v[14:15] neg_lo:[0,1] neg_hi:[0,1]
	v_mov_b32_e32 v8, v7
	v_pk_mul_f32 v[2:3], v[8:9], v[2:3]
	ds_read_b128 v[6:9], v185
	v_pk_fma_f32 v[14:15], v[98:99], v[2:3], v[100:101]
	v_cvt_pk_bf16_f32 v2, v10, v11
	v_cvt_pk_bf16_f32 v3, v12, v13
	ds_read_b128 v[10:13], v186
	v_cvt_pk_bf16_f32 v4, v4, v5
	v_cvt_pk_bf16_f32 v5, v14, v15
	v_lshlrev_b32_e32 v15, 16, v20
	v_lshlrev_b32_e32 v14, 16, v24
	s_waitcnt lgkmcnt(1)
	v_mov_b32_e32 v16, v6
	v_mov_b32_e32 v17, v8
	v_pk_add_f32 v[14:15], v[14:15], v[16:17] neg_lo:[0,1] neg_hi:[0,1]
	v_mov_b32_e32 v8, v7
	v_pk_mul_f32 v[6:7], v[8:9], v[14:15]
	s_waitcnt lgkmcnt(0)
	v_mov_b32_e32 v8, v10
	v_pk_fma_f32 v[14:15], v[98:99], v[6:7], v[100:101]
	v_lshlrev_b32_e32 v7, 16, v21
	v_lshlrev_b32_e32 v6, 16, v25
	v_mov_b32_e32 v9, v12
	v_pk_add_f32 v[16:17], v[6:7], v[8:9] neg_lo:[0,1] neg_hi:[0,1]
	ds_read_u16 v19, v187 offset:34816
	ds_read_u16 v20, v187 offset:35336
	ds_read_u16 v21, v187 offset:42096
	ds_read_b128 v[6:9], v188
	v_mov_b32_e32 v12, v11
	v_pk_mul_f32 v[10:11], v[12:13], v[16:17]
	v_lshlrev_b32_e32 v13, 16, v22
	s_waitcnt lgkmcnt(3)
	v_lshlrev_b32_e32 v12, 16, v19
	s_waitcnt lgkmcnt(0)
	v_mov_b32_e32 v16, v6
	v_mov_b32_e32 v17, v8
	v_pk_add_f32 v[12:13], v[12:13], v[16:17] neg_lo:[0,1] neg_hi:[0,1]
	v_mov_b32_e32 v8, v7
	v_pk_mul_f32 v[6:7], v[8:9], v[12:13]
	v_pk_fma_f32 v[10:11], v[98:99], v[10:11], v[100:101]
	v_pk_fma_f32 v[12:13], v[98:99], v[6:7], v[100:101]
	ds_read_b128 v[6:9], v189
	ds_read_u16 v16, v18 offset:44956
	ds_read_u16 v22, v18 offset:51716
	ds_read_u16 v23, v18 offset:52236
	ds_read_u16 v24, v18 offset:52756
	ds_read_u16 v26, v18 offset:53276
	ds_read_u16 v27, v18 offset:60036
	ds_read_u16 v28, v18 offset:60556
	ds_read_u16 v36, v18 offset:61076
	s_waitcnt lgkmcnt(7)
	v_lshlrev_b32_e32 v17, 16, v16
	v_lshlrev_b32_e32 v16, 16, v20
	v_mov_b32_e32 v18, v6
	v_mov_b32_e32 v19, v8
	v_pk_add_f32 v[16:17], v[16:17], v[18:19] neg_lo:[0,1] neg_hi:[0,1]
	v_mov_b32_e32 v8, v7
	v_pk_mul_f32 v[6:7], v[8:9], v[16:17]
	ds_read_u16 v25, v187 offset:42616
	ds_read_u16 v29, v187 offset:43136
	v_pk_fma_f32 v[16:17], v[98:99], v[6:7], v[100:101]
	v_cvt_pk_bf16_f32 v7, v10, v11
	v_cvt_pk_bf16_f32 v8, v12, v13
	ds_read_b128 v[10:13], v190
	v_cvt_pk_bf16_f32 v6, v14, v15
	v_cvt_pk_bf16_f32 v9, v16, v17
	ds_read_b128 v[14:17], v191
	s_waitcnt lgkmcnt(10)
	v_lshlrev_b32_e32 v19, 16, v22
	v_lshlrev_b32_e32 v18, 16, v21
	s_waitcnt lgkmcnt(1)
	v_mov_b32_e32 v20, v10
	v_mov_b32_e32 v21, v12
	v_pk_add_f32 v[18:19], v[18:19], v[20:21] neg_lo:[0,1] neg_hi:[0,1]
	v_mov_b32_e32 v12, v11
	v_pk_mul_f32 v[10:11], v[12:13], v[18:19]
	s_waitcnt lgkmcnt(0)
	v_mov_b32_e32 v12, v14
	v_pk_fma_f32 v[18:19], v[98:99], v[10:11], v[100:101]
	v_lshlrev_b32_e32 v11, 16, v23
	v_lshlrev_b32_e32 v10, 16, v25
	v_mov_b32_e32 v13, v16
	v_pk_add_f32 v[10:11], v[10:11], v[12:13] neg_lo:[0,1] neg_hi:[0,1]
	v_mov_b32_e32 v16, v15
	v_pk_mul_f32 v[14:15], v[16:17], v[10:11]
	ds_read_b128 v[10:13], v192
	v_pk_fma_f32 v[20:21], v[98:99], v[14:15], v[100:101]
	ds_read_b128 v[14:17], v194
	v_lshlrev_b32_e32 v23, 16, v24
	v_lshlrev_b32_e32 v22, 16, v29
	s_waitcnt lgkmcnt(1)
	v_mov_b32_e32 v24, v10
	v_mov_b32_e32 v25, v12
	v_pk_add_f32 v[22:23], v[22:23], v[24:25] neg_lo:[0,1] neg_hi:[0,1]
	v_mov_b32_e32 v12, v11
	v_pk_mul_f32 v[10:11], v[12:13], v[22:23]
	s_waitcnt lgkmcnt(0)
	v_mov_b32_e32 v22, v14
	v_pk_fma_f32 v[12:13], v[98:99], v[10:11], v[100:101]
	ds_read_u16 v10, v193 offset:34816
	ds_read_u16 v24, v193 offset:41576
	ds_read_u16 v29, v193 offset:42096
	ds_read_u16 v38, v193 offset:42616
	ds_read_u16 v121, v193 offset:43136
	v_lshlrev_b32_e32 v11, 16, v26
	s_waitcnt lgkmcnt(4)
; #define LAS __attribute__((address_space(3)))
; #define MFMA16(A, B, Cc) __builtin_amdgcn_mfma_f32_16x16x32_bf16((A), (B), (Cc), 0, 0, 0)
; #define PIN(x) asm volatile("" : "+v"(x))
; __device__ __forceinline__ float bf_lo(unsigned w) { return __uint_as_float(w << 16); }
; __device__ __forceinline__ unsigned pk4f8(float a, float b, float c, float d) { int p = __builtin_amdgcn_cvt_pk_fp8_f32(sat8(a), sat8(b), 0, false); p = __builtin_amdgcn_cvt_pk_fp8_f32(sat8(c), sat8(d), p, true); return (unsigned)p; }
; __device__ __forceinline__ float bf_hi(unsigned w) { return __uint_as_float(w & 0xffff0000u); }
; __device__ __forceinline__ void gmlp_compute(GmlpRegs& R, const Args& a, const Ctx& C, int c, int hd) {
;     ...
;     f32x4 acc[8];
; #pragma unroll
;     for (int nt = 0; nt < 8; ++nt) { acc[nt] = (f32x4){0.f, 0.f, 0.f, 0.f};
; #pragma unroll
;         for (int ks = 0; ks <= nt / 2; ++ks) acc[nt] = MFMA16(af[ks], *(const LAS bf16x8*)(WL + (16 * nt + fr) * 272 + (32 * ks + 8 * q) * 2), acc[nt]); }
; #pragma unroll
;     for (int nt = 0; nt < 8; ++nt) PIN(R.uq[nt]);
; #pragma unroll
;     for (int nt = 0; nt < 8; ++nt) { const size_t row = T0 + 16 * nt + fr; const float bs = R.bsv[nt];
;         const float o0 = bf_lo(R.uq[nt].x) * (acc[nt][0] + bs), o1 = bf_hi(R.uq[nt].x) * (acc[nt][1] + bs);
;         const float o2 = bf_lo(R.uq[nt].y) * (acc[nt][2] + bs), o3 = bf_hi(R.uq[nt].y) * (acc[nt][3] + bs);
;         *(unsigned*)((unsigned char*)Y + row * DM + chs) = pk4f8(o0, o1, o2, o3); }
	v_lshlrev_b32_e32 v10, 16, v10
	v_mov_b32_e32 v23, v16
	v_pk_add_f32 v[10:11], v[10:11], v[22:23] neg_lo:[0,1] neg_hi:[0,1]
	v_mov_b32_e32 v16, v15
	v_pk_mul_f32 v[10:11], v[16:17], v[10:11]
	ds_read_b128 v[14:17], v195
	v_pk_fma_f32 v[22:23], v[98:99], v[10:11], v[100:101]
	v_cvt_pk_bf16_f32 v10, v18, v19
	v_cvt_pk_bf16_f32 v11, v20, v21
	v_cvt_pk_bf16_f32 v12, v12, v13
	v_cvt_pk_bf16_f32 v13, v22, v23
	v_lshlrev_b32_e32 v23, 16, v27
	s_waitcnt lgkmcnt(4)
	v_lshlrev_b32_e32 v22, 16, v24
	ds_read_b128 v[18:21], v196
	s_waitcnt lgkmcnt(1)
	v_mov_b32_e32 v24, v14
	v_mov_b32_e32 v25, v16
	v_pk_add_f32 v[26:27], v[22:23], v[24:25] neg_lo:[0,1] neg_hi:[0,1]
	v_mov_b32_e32 v16, v15
	v_add_u32_e32 v126, v199, v200
	v_pk_mul_f32 v[14:15], v[16:17], v[26:27]
	v_lshlrev_b32_e32 v31, 16, v28
	v_lshlrev_b32_e32 v30, 16, v29
	ds_read_b128 v[26:29], v126 offset:8704
	s_waitcnt lgkmcnt(1)
	v_mov_b32_e32 v32, v18
	v_mov_b32_e32 v33, v20
	v_pk_add_f32 v[34:35], v[30:31], v[32:33] neg_lo:[0,1] neg_hi:[0,1]
	ds_read_b128 v[30:33], v126 offset:8768
	v_mov_b32_e32 v20, v19
	s_waitcnt lgkmcnt(1)
	v_mfma_f32_16x16x32_bf16 v[26:29], v[2:5], v[26:29], 0
	v_mul_f32_e64 v34, v20, v34
	v_mul_f32_e64 v35, v21, v35
	ds_read_b128 v[18:21], v126 offset:13056
	v_lshlrev_b32_e32 v46, 16, v38
	ds_read_b128 v[38:41], v126 offset:17408
	ds_read_b128 v[42:45], v126 offset:17472
	s_waitcnt lgkmcnt(3)
	v_mfma_f32_16x16x32_bf16 v[26:29], v[6:9], v[30:33], v[26:29]
	v_fma_f32 v92, v98, v34, v100
	v_fma_f32 v93, v99, v35, v101
	v_lshlrev_b32_e32 v47, 16, v36
	ds_read_b128 v[30:33], v126 offset:13120
	ds_read_b128 v[34:37], v197
	s_waitcnt lgkmcnt(4)
	v_mfma_f32_16x16x32_bf16 v[18:21], v[2:5], v[18:21], 0
	v_fma_f32 v88, v98, v14, v100
	v_fma_f32 v89, v99, v15, v101
	ds_read_b128 v[22:25], v126
	ds_read_b128 v[14:17], v126 offset:4352
	s_waitcnt lgkmcnt(5)
	v_mfma_f32_16x16x32_bf16 v[38:41], v[2:5], v[38:41], 0
	s_lshl_b64 s[4:5], s[70:71], 11
	s_mov_b64 s[8:9], 0x2300000
	v_readlane_b32 s16, v249, 1
	s_waitcnt lgkmcnt(3)
	v_mfma_f32_16x16x32_bf16 v[18:21], v[6:9], v[30:33], v[18:21]
	ds_read_b128 v[30:33], v198
	s_waitcnt lgkmcnt(3)
	v_mov_b32_e32 v48, v34
	v_mov_b32_e32 v49, v36
	v_pk_add_f32 v[90:91], v[46:47], v[48:49] neg_lo:[0,1] neg_hi:[0,1]
	v_mov_b32_e32 v36, v35
	ds_read_b128 v[46:49], v126 offset:17536
	v_mfma_f32_16x16x32_bf16 v[38:41], v[6:9], v[42:45], v[38:41]
	v_mul_f32_e64 v42, v36, v90
	v_mul_f32_e64 v43, v37, v91
	ds_read_b128 v[34:37], v126 offset:21760
	v_pk_fma_f32 v[122:123], v[98:99], v[42:43], v[100:101]
	ds_read_b128 v[42:45], v126 offset:21824
	s_waitcnt lgkmcnt(1)
	v_mfma_f32_16x16x32_bf16 v[34:37], v[2:5], v[34:37], 0
	v_lshlrev_b32_e32 v91, 16, v113
	v_lshlrev_b32_e32 v90, 16, v121
	v_mov_b32_e32 v124, v30
	v_mfma_f32_16x16x32_bf16 v[38:41], v[10:13], v[46:49], v[38:41]
	ds_read_b128 v[46:49], v126 offset:21888
	v_mov_b32_e32 v125, v32
	v_pk_add_f32 v[90:91], v[90:91], v[124:125] neg_lo:[0,1] neg_hi:[0,1]
	s_waitcnt lgkmcnt(1)
	v_mfma_f32_16x16x32_bf16 v[34:37], v[6:9], v[42:45], v[34:37]
	ds_read_b128 v[42:45], v126 offset:26112
	v_mov_b32_e32 v32, v31
	v_readlane_b32 s17, v249, 2
	s_waitcnt lgkmcnt(1)
	v_mfma_f32_16x16x32_bf16 v[34:37], v[10:13], v[46:49], v[34:37]
	v_mul_f32_e64 v46, v32, v90
	v_mul_f32_e64 v47, v33, v91
	ds_read_b128 v[30:33], v126 offset:26176
	v_pk_fma_f32 v[98:99], v[98:99], v[46:47], v[100:101]
	s_waitcnt lgkmcnt(1)
	v_mfma_f32_16x16x32_bf16 v[42:45], v[2:5], v[42:45], 0
	v_cvt_pk_bf16_f32 v46, v88, v89
	ds_read_b128 v[88:91], v126 offset:26240
	v_cvt_pk_bf16_f32 v47, v92, v93
	s_waitcnt lgkmcnt(1)
	v_mfma_f32_16x16x32_bf16 v[30:33], v[6:9], v[30:33], v[42:45]
	v_cvt_pk_bf16_f32 v48, v122, v123
	v_cvt_pk_bf16_f32 v49, v98, v99
	v_readlane_b32 s18, v249, 3
	ds_read_b128 v[42:45], v126 offset:26304
	s_waitcnt lgkmcnt(1)
	v_mfma_f32_16x16x32_bf16 v[30:33], v[10:13], v[88:91], v[30:33]
	v_readlane_b32 s19, v249, 4
	v_readlane_b32 s20, v249, 5
	v_readlane_b32 s21, v249, 6
	s_waitcnt lgkmcnt(0)
	v_mfma_f32_16x16x32_bf16 v[30:33], v[46:49], v[42:45], v[30:33]
	ds_read_b128 v[42:45], v126 offset:30464
	ds_read_b128 v[88:91], v126 offset:30528
	v_readlane_b32 s22, v249, 7
	v_readlane_b32 s23, v249, 8
	v_mfma_f32_16x16x32_bf16 v[22:25], v[2:5], v[22:25], 0
	v_readlane_b32 s24, v249, 9
	v_readlane_b32 s25, v249, 10
	v_readlane_b32 s26, v249, 11
	v_mfma_f32_16x16x32_bf16 v[14:17], v[2:5], v[14:17], 0
	v_readlane_b32 s27, v249, 12
	v_readlane_b32 s28, v249, 13
	v_readlane_b32 s29, v249, 14
	s_waitcnt lgkmcnt(1)
	v_mfma_f32_16x16x32_bf16 v[2:5], v[2:5], v[42:45], 0
	v_readlane_b32 s30, v249, 15
	v_readlane_b32 s31, v249, 16
	s_mov_b64 s[14:15], s[22:23]
	s_waitcnt lgkmcnt(0)
	v_mfma_f32_16x16x32_bf16 v[2:5], v[6:9], v[88:91], v[2:5]
	ds_read_b128 v[6:9], v126 offset:30592
	ds_read_b128 v[42:45], v126 offset:30656
	s_waitcnt vmcnt(23)
	s_waitcnt vmcnt(22)
	s_waitcnt lgkmcnt(1)
	v_mfma_f32_16x16x32_bf16 v[2:5], v[10:13], v[6:9], v[2:5]
	v_lshlrev_b32_e32 v6, 16, v110
	v_add_f32_e32 v7, v161, v22
	v_mul_f32_e32 v6, v7, v6
	v_and_b32_e32 v7, 0xffff0000, v110
	v_add_f32_e32 v8, v161, v23
	v_mul_f32_e32 v7, v8, v7
	v_med3_f32 v6, v6, s1, v128
	v_med3_f32 v7, v7, s1, v128
	v_mov_b32_e32 v11, 0
	v_lshlrev_b32_e32 v8, 16, v111
	v_add_f32_e32 v9, v161, v24
	v_cvt_pk_fp8_f32 v11, v6, v7
	v_mul_f32_e32 v8, v9, v8
	v_and_b32_e32 v9, 0xffff0000, v111
	v_add_f32_e32 v10, v161, v25
	v_mul_f32_e32 v6, v10, v9
	v_med3_f32 v7, v8, s1, v128
	v_med3_f32 v6, v6, s1, v128
	v_cvt_pk_fp8_f32 v11, v7, v6 op_sel:[0,0,1]
	v_lshlrev_b32_e32 v8, 16, v118
	v_add_f32_e32 v9, v160, v14
	v_mul_f32_e32 v8, v9, v8
	v_and_b32_e32 v9, 0xffff0000, v118
	v_add_f32_e32 v10, v160, v15
	v_lshlrev_b64 v[6:7], 11, v[116:117]
	v_mul_f32_e32 v9, v10, v9
	v_lshl_add_u64 v[6:7], v[142:143], 0, v[6:7]
	v_med3_f32 v8, v8, s1, v128
	v_med3_f32 v9, v9, s1, v128
	v_mov_b32_e32 v13, 0
	s_waitcnt vmcnt(21)
; __device__ __forceinline__ float bf_lo(unsigned w) { return __uint_as_float(w << 16); }
; __device__ __forceinline__ unsigned pk4f8(float a, float b, float c, float d) { int p = __builtin_amdgcn_cvt_pk_fp8_f32(sat8(a), sat8(b), 0, false); p = __builtin_amdgcn_cvt_pk_fp8_f32(sat8(c), sat8(d), p, true); return (unsigned)p; }
; __device__ __forceinline__ float bf_hi(unsigned w) { return __uint_as_float(w & 0xffff0000u); }
; __device__ __forceinline__ void s5_prompt_task(const Args& a, const Ctx& C, int b, int g, v4u (&xv)[8]) {
;     ...
;     const size_t row0 = (size_t)b * SEQ;
;     const bf16* XBg = (const bf16*)(a.ws + WS_XB) + ((size_t)g * MP + row0) * 16; const bf16* ZBg = (const bf16*)(a.ws + WS_ZB) + ((size_t)g * MP + row0) * 16;
;     __syncthreads();
; __device__ __forceinline__ void gmlp_compute(GmlpRegs& R, const Args& a, const Ctx& C, int c, int hd) {
;     ...
;     for (int nt = 0; nt < 8; ++nt) { const size_t row = T0 + 16 * nt + fr; const float bs = R.bsv[nt];
;         const float o0 = bf_lo(R.uq[nt].x) * (acc[nt][0] + bs), o1 = bf_hi(R.uq[nt].x) * (acc[nt][1] + bs);
;         const float o2 = bf_lo(R.uq[nt].y) * (acc[nt][2] + bs), o3 = bf_hi(R.uq[nt].y) * (acc[nt][3] + bs);
;         *(unsigned*)((unsigned char*)Y + row * DM + chs) = pk4f8(o0, o1, o2, o3); }
	s_waitcnt vmcnt(20)
	s_waitcnt vmcnt(19)
	s_waitcnt vmcnt(18)
	s_waitcnt vmcnt(17)
	s_waitcnt vmcnt(16)
	global_store_dword v[6:7], v11, off
	v_lshlrev_b32_e32 v10, 16, v119
	v_add_f32_e32 v11, v160, v16
	v_cvt_pk_fp8_f32 v13, v8, v9
	v_mul_f32_e32 v10, v11, v10
	v_and_b32_e32 v11, 0xffff0000, v119
	v_add_f32_e32 v12, v160, v17
	v_mul_f32_e32 v8, v12, v11
	v_med3_f32 v9, v10, s1, v128
	v_med3_f32 v8, v8, s1, v128
	v_cvt_pk_fp8_f32 v13, v9, v8 op_sel:[0,0,1]
	v_add_co_u32_e32 v8, vcc, s2, v6
	v_add_f32_e32 v10, v159, v27
	s_nop 0
	v_addc_co_u32_e32 v9, vcc, 0, v7, vcc
	global_store_dword v[8:9], v13, off
	v_lshlrev_b32_e32 v8, 16, v114
	v_add_f32_e32 v9, v159, v26
	v_mul_f32_e32 v8, v9, v8
	v_and_b32_e32 v9, 0xffff0000, v114
	v_mul_f32_e32 v9, v10, v9
	v_med3_f32 v8, v8, s1, v128
	v_med3_f32 v9, v9, s1, v128
	v_mov_b32_e32 v13, 0
	v_lshlrev_b32_e32 v10, 16, v115
	v_add_f32_e32 v11, v159, v28
	v_cvt_pk_fp8_f32 v13, v8, v9
	v_mul_f32_e32 v10, v11, v10
	v_and_b32_e32 v11, 0xffff0000, v115
	v_add_f32_e32 v12, v159, v29
	v_mul_f32_e32 v8, v12, v11
	v_med3_f32 v9, v10, s1, v128
	v_med3_f32 v8, v8, s1, v128
	v_cvt_pk_fp8_f32 v13, v9, v8 op_sel:[0,0,1]
	v_add_co_u32_e32 v8, vcc, s33, v6
	v_add_f32_e32 v10, v156, v19
	s_nop 0
	v_addc_co_u32_e32 v9, vcc, 0, v7, vcc
	global_store_dword v[8:9], v13, off
	v_lshlrev_b32_e32 v8, 16, v108
	v_add_f32_e32 v9, v156, v18
	v_mul_f32_e32 v8, v9, v8
	v_and_b32_e32 v9, 0xffff0000, v108
	v_mul_f32_e32 v9, v10, v9
	v_med3_f32 v8, v8, s1, v128
	v_med3_f32 v9, v9, s1, v128
	v_mov_b32_e32 v13, 0
	v_lshlrev_b32_e32 v10, 16, v109
	v_add_f32_e32 v11, v156, v20
	v_cvt_pk_fp8_f32 v13, v8, v9
	v_mul_f32_e32 v10, v11, v10
	v_and_b32_e32 v11, 0xffff0000, v109
	v_add_f32_e32 v12, v156, v21
	v_mul_f32_e32 v8, v12, v11
	v_med3_f32 v9, v10, s1, v128
	v_med3_f32 v8, v8, s1, v128
	v_cvt_pk_fp8_f32 v13, v9, v8 op_sel:[0,0,1]
	v_add_co_u32_e32 v8, vcc, s74, v6
	v_add_f32_e32 v10, v154, v39
	s_nop 0
	v_addc_co_u32_e32 v9, vcc, 0, v7, vcc
	global_store_dword v[8:9], v13, off
	v_lshlrev_b32_e32 v8, 16, v106
	v_add_f32_e32 v9, v154, v38
	v_mul_f32_e32 v8, v9, v8
	v_and_b32_e32 v9, 0xffff0000, v106
	v_mul_f32_e32 v9, v10, v9
	v_med3_f32 v8, v8, s1, v128
	v_med3_f32 v9, v9, s1, v128
	v_mov_b32_e32 v13, 0
	v_lshlrev_b32_e32 v10, 16, v107
	v_add_f32_e32 v11, v154, v40
	v_cvt_pk_fp8_f32 v13, v8, v9
	v_mul_f32_e32 v10, v11, v10
	v_and_b32_e32 v11, 0xffff0000, v107
	v_add_f32_e32 v12, v154, v41
	v_mul_f32_e32 v8, v12, v11
	v_med3_f32 v9, v10, s1, v128
	v_med3_f32 v8, v8, s1, v128
	v_cvt_pk_fp8_f32 v13, v9, v8 op_sel:[0,0,1]
	v_add_co_u32_e32 v8, vcc, s75, v6
	v_add_f32_e32 v10, v152, v35
	s_nop 0
	v_addc_co_u32_e32 v9, vcc, 0, v7, vcc
	global_store_dword v[8:9], v13, off
	v_lshlrev_b32_e32 v8, 16, v104
	v_add_f32_e32 v9, v152, v34
	v_mul_f32_e32 v8, v9, v8
	v_and_b32_e32 v9, 0xffff0000, v104
	v_mul_f32_e32 v9, v10, v9
	v_med3_f32 v8, v8, s1, v128
	v_med3_f32 v9, v9, s1, v128
	v_mov_b32_e32 v13, 0
	v_lshlrev_b32_e32 v10, 16, v105
	v_add_f32_e32 v11, v152, v36
	v_cvt_pk_fp8_f32 v13, v8, v9
	v_mul_f32_e32 v10, v11, v10
	v_and_b32_e32 v11, 0xffff0000, v105
	v_add_f32_e32 v12, v152, v37
	v_mul_f32_e32 v8, v12, v11
	v_med3_f32 v9, v10, s1, v128
	v_med3_f32 v8, v8, s1, v128
	v_cvt_pk_fp8_f32 v13, v9, v8 op_sel:[0,0,1]
	v_add_co_u32_e32 v8, vcc, s76, v6
	v_add_f32_e32 v10, v151, v31
	s_nop 0
	v_addc_co_u32_e32 v9, vcc, 0, v7, vcc
	global_store_dword v[8:9], v13, off
	v_lshlrev_b32_e32 v8, 16, v102
	v_add_f32_e32 v9, v151, v30
	v_mul_f32_e32 v8, v9, v8
	v_and_b32_e32 v9, 0xffff0000, v102
	v_mul_f32_e32 v9, v10, v9
	v_med3_f32 v8, v8, s1, v128
	v_med3_f32 v9, v9, s1, v128
	v_mov_b32_e32 v13, 0
	v_lshlrev_b32_e32 v10, 16, v103
	v_add_f32_e32 v11, v151, v32
	v_cvt_pk_fp8_f32 v13, v8, v9
	v_mul_f32_e32 v10, v11, v10
	v_and_b32_e32 v11, 0xffff0000, v103
	v_add_f32_e32 v12, v151, v33
	v_mul_f32_e32 v8, v12, v11
	v_med3_f32 v9, v10, s1, v128
	v_med3_f32 v8, v8, s1, v128
	s_waitcnt lgkmcnt(0)
	v_mfma_f32_16x16x32_bf16 v[2:5], v[46:49], v[42:45], v[2:5]
	v_cvt_pk_fp8_f32 v13, v9, v8 op_sel:[0,0,1]
	v_add_co_u32_e32 v8, vcc, s77, v6
	v_mov_b32_e32 v111, 0
	s_nop 0
	v_addc_co_u32_e32 v9, vcc, 0, v7, vcc
	global_store_dword v[8:9], v13, off
	v_lshlrev_b32_e32 v8, 16, v96
	s_nop 0
	v_add_f32_e32 v2, v150, v2
	v_mul_f32_e32 v2, v2, v8
	v_and_b32_e32 v8, 0xffff0000, v96
	v_add_f32_e32 v3, v150, v3
	v_mul_f32_e32 v3, v3, v8
	v_lshlrev_b32_e32 v8, 16, v97
	v_add_f32_e32 v4, v150, v4
	v_mul_f32_e32 v4, v4, v8
	v_and_b32_e32 v8, 0xffff0000, v97
	v_add_f32_e32 v5, v150, v5
	v_med3_f32 v2, v2, s1, v128
	v_med3_f32 v3, v3, s1, v128
	v_mov_b32_e32 v9, 0
	v_cvt_pk_fp8_f32 v9, v2, v3
	v_mul_f32_e32 v2, v5, v8
	v_med3_f32 v3, v4, s1, v128
	v_med3_f32 v2, v2, s1, v128
	s_mul_i32 s1, s0, 0x2100
	s_add_u32 s4, s1, s4
	s_addc_u32 s5, 0, s5
	s_lshl_b64 s[4:5], s[4:5], 5
	s_lshl_b32 s1, s0, 9
	s_lshl_b32 s2, s0, 12
	s_add_u32 s6, s94, s1
	v_cvt_pk_fp8_f32 v9, v3, v2 op_sel:[0,0,1]
	v_add_co_u32_e32 v2, vcc, s78, v6
	v_lshlrev_b32_e32 v110, 2, v153
	s_addc_u32 s7, s95, 0
	v_addc_co_u32_e32 v3, vcc, 0, v7, vcc
	v_lshl_add_u64 v[18:19], s[6:7], 0, v[110:111]
	s_mov_b32 s1, 0x2300000
	v_lshl_add_u64 v[20:21], v[18:19], 0, s[8:9]
	v_add_co_u32_e32 v18, vcc, s1, v18
	global_store_dword v[2:3], v9, off
	s_nop 0
	v_addc_co_u32_e32 v19, vcc, 0, v19, vcc
	s_barrier
; __device__ __forceinline__ unsigned pk2(float lo, float hi) { return pg8::cvt_pk_bf16(lo, hi); }
; __device__ __forceinline__ bf16x8 pack8(f32x4 lo, f32x4 hi) { v4u w; w.x = pk2(lo[0], lo[1]); w.y = pk2(lo[2], lo[3]); w.z = pk2(hi[0], hi[1]); w.w = pk2(hi[2], hi[3]); return __builtin_bit_cast(bf16x8, w); }
; __device__ __forceinline__ void s5_load_consts(S5C& K, const Args& a, int g, int lane) {
;     const int fr = lane & 15, q = lane >> 4;
;     const float* ABAR = (const float*)(a.ws + WS_S5C + S5C_ABAR) + (size_t)g * 128;
;     const bf16* BBAR = (const bf16*)(a.ws + WS_S5C + S5C_BBAR) + (size_t)g * 2048;
; #pragma unroll
;     for (int j = 0; j < 4; ++j) { const f32x4 x0 = *(const f32x4*)(ABAR + 2 * (16 * j + 4 * q)), x1 = *(const f32x4*)(ABAR + 2 * (16 * j + 4 * q) + 4);
;         K.ar[j] = (f32x4){x0[0], x0[2], x1[0], x1[2]}; K.ai[j] = (f32x4){x0[1], x0[3], x1[1], x1[3]}; }
; #pragma unroll
;     for (int mt = 0; mt < 8; ++mt) K.Bf[mt] = *(const v2u*)(BBAR + (mt * 16 + fr) * 16 + 4 * q);
;     const float* cre = a.in[I_CRE] + ((size_t)g * 16 + fr) * 64; const float* cim = a.in[I_CIM] + ((size_t)g * 16 + fr) * 64;
; #pragma unroll
;     for (int j = 0; j < 4; ++j) { const f32x4 r4 = *(const f32x4*)(cre + 16 * j + 4 * q), i4 = *(const f32x4*)(cim + 16 * j + 4 * q); K.Cf[j] = pack8(r4, -i4); }
;     const float* wg = a.in[I_WGLU] + (size_t)g * 512;
;     { f32x4 v, gt;
; #pragma unroll
;       for (int e = 0; e < 4; ++e) { v[e] = wg[(4 * q + e) * 32 + fr]; gt[e] = wg[(4 * q + e) * 32 + 16 + fr]; }
;       K.Wv = (v2u){pk2(v[0], v[1]), pk2(v[2], v[3])}; K.Wg = (v2u){pk2(gt[0], gt[1]), pk2(gt[2], gt[3])}; }
;     K.dsk = *(const f32x4*)(a.in[I_DSKIP] + g * 16 + 4 * q);
;     K.bv = *(const f32x4*)(a.in[I_BGLU] + g * 32 + 4 * q); K.bg = *(const f32x4*)(a.in[I_BGLU] + g * 32 + 16 + 4 * q);
; }
; __device__ __forceinline__ void s5_prompt_task(const Args& a, const Ctx& C, int b, int g, v4u (&xv)[8]) {
;     ...
;     { const float* A16 = (const float*)(a.ws + WS_S5C + S5C_A16) + (size_t)g * 128; const float* A256 = (const float*)(a.ws + WS_S5C + S5C_A256) + (size_t)g * 128;
;       const float a16r = A16[2 * lane], a16i = A16[2 * lane + 1], a256r = A256[2 * lane], a256i = A256[2 * lane + 1];
	s_waitcnt vmcnt(15)
	s_waitcnt vmcnt(14)
	s_waitcnt vmcnt(13)
	s_waitcnt vmcnt(12)
	s_waitcnt vmcnt(11)
	s_waitcnt vmcnt(10)
	s_waitcnt vmcnt(9)
	s_waitcnt vmcnt(8)
	global_load_dwordx4 v[2:5], v[20:21], off offset:16
	global_load_dwordx4 v[6:9], v[20:21], off offset:144
	global_load_dwordx4 v[10:13], v[20:21], off offset:272
	global_load_dwordx4 v[14:17], v[20:21], off offset:400
	global_load_dwordx4 v[30:33], v[18:19], off
	v_and_b32_e32 v18, 0x1fe0, v94
	v_lshrrev_b32_e32 v19, 1, v0
	v_add_u32_e32 v18, 0, v18
	v_and_b32_e32 v19, 0xf0, v19
	v_and_b32_e32 v24, 16, v94
	v_add3_u32 v18, v18, v19, v24
	ds_write_b128 v18, v[74:77]
	v_and_b32_e32 v18, 0x3fe0, v87
	v_lshrrev_b32_e32 v19, 1, v146
	v_add_u32_e32 v18, 0, v18
	v_and_b32_e32 v19, 0x1f0, v19
	v_add3_u32 v18, v18, v19, v24
	ds_write_b128 v18, v[78:81]
	v_and_b32_e32 v18, 0x7fe0, v148
	v_lshrrev_b32_e32 v19, 1, v147
	v_add_u32_e32 v18, 0, v18
	v_and_b32_e32 v19, 0x3f0, v19
	v_add3_u32 v18, v18, v19, v24
	ds_write_b128 v18, v[70:73]
	v_and_b32_e32 v18, 0x7fe0, v86
	v_lshrrev_b32_e32 v19, 1, v95
	v_add_u32_e32 v18, 0, v18
	v_and_b32_e32 v19, 0x3f0, v19
	v_add3_u32 v18, v18, v19, v24
	ds_write_b128 v18, v[66:69]
	v_and_b32_e32 v18, 0xbfe0, v85
	v_lshrrev_b32_e32 v19, 1, v120
	v_add_u32_e32 v18, 0, v18
	v_and_b32_e32 v19, 0x5f0, v19
	v_add3_u32 v18, v18, v19, v24
	ds_write_b128 v18, v[58:61]
	v_and_b32_e32 v18, 0xffe0, v84
	v_lshrrev_b32_e32 v19, 1, v157
	v_add_u32_e32 v18, 0, v18
	v_and_b32_e32 v19, 0x7f0, v19
	v_add3_u32 v18, v18, v19, v24
	ds_write_b128 v18, v[62:65]
	v_and_b32_e32 v18, 0xffe0, v83
	v_lshrrev_b32_e32 v19, 1, v158
	s_add_u32 s8, s94, s2
	v_add_u32_e32 v18, 0, v18
	v_and_b32_e32 v19, 0x7f0, v19
	s_addc_u32 s9, s95, 0
	v_lshlrev_b32_e32 v110, 1, v112
	v_add3_u32 v25, v18, v19, v24
	v_lshl_add_u64 v[18:19], s[8:9], 0, v[110:111]
	v_lshlrev_b32_e32 v22, 5, v149
	v_mov_b32_e32 v23, v111
	v_lshl_add_u64 v[18:19], v[18:19], 0, v[22:23]
	s_mov_b32 s1, 0x2320000
	v_add_co_u32_e32 v22, vcc, s1, v18
	s_mov_b64 s[8:9], 0x2320000
	s_nop 0
	v_addc_co_u32_e32 v23, vcc, 0, v19, vcc
	global_load_dwordx2 v[114:115], v[22:23], off
	v_lshl_add_u64 v[18:19], v[18:19], 0, s[8:9]
	global_load_dwordx2 v[116:117], v[18:19], off offset:512
	global_load_dwordx4 v[70:73], v[20:21], off offset:128
	v_and_b32_e32 v22, 0xffe0, v82
	v_lshrrev_b32_e32 v23, 1, v155
	global_load_dwordx4 v[74:77], v[20:21], off offset:256
	global_load_dwordx4 v[66:69], v[20:21], off offset:384
	v_add_u32_e32 v22, 0, v22
	v_and_b32_e32 v23, 0x7f0, v23
	v_add3_u32 v22, v22, v23, v24
	ds_write_b128 v25, v[50:53]
	ds_write_b128 v22, v[54:57]
	global_load_dwordx2 v[126:127], v[18:19], off offset:1024
	global_load_dwordx2 v[128:129], v[18:19], off offset:1536
	global_load_dwordx2 v[130:131], v[18:19], off offset:2048
	global_load_dwordx2 v[132:133], v[18:19], off offset:2560
	global_load_dwordx2 v[134:135], v[18:19], off offset:3072
	global_load_dwordx2 v[136:137], v[18:19], off offset:3584
	v_lshl_or_b32 v18, v149, 8, s2
	v_mov_b32_e32 v19, v111
	s_mov_b64 s[16:17], s[24:25]
	v_lshl_add_u64 v[20:21], s[14:15], 0, v[18:19]
	v_lshl_add_u64 v[18:19], s[16:17], 0, v[18:19]
	v_lshlrev_b32_e32 v78, 2, v112
	v_mov_b32_e32 v79, v111
	s_mov_b64 s[20:21], s[28:29]
	v_lshl_add_u64 v[20:21], v[20:21], 0, v[78:79]
	v_lshl_add_u64 v[18:19], v[18:19], 0, v[78:79]
	s_lshl_b32 s1, s0, 11
	global_load_dwordx4 v[58:61], v[20:21], off
	global_load_dwordx4 v[50:53], v[20:21], off offset:64
	global_load_dwordx4 v[62:65], v[18:19], off
	global_load_dwordx4 v[54:57], v[18:19], off offset:64
	global_load_dwordx4 v[42:45], v[20:21], off offset:128
	global_load_dwordx4 v[34:37], v[20:21], off offset:192
	global_load_dwordx4 v[46:49], v[18:19], off offset:128
	global_load_dwordx4 v[38:41], v[18:19], off offset:192
	s_add_u32 s8, s20, s1
	v_lshlrev_b32_e32 v18, 2, v149
	s_mov_b64 s[18:19], s[26:27]
	s_addc_u32 s9, s21, 0
	v_lshl_or_b32 v18, v145, 9, v18
	s_lshl_b32 s1, s0, 4
	s_lshl_b32 s2, s0, 6
	global_load_dword v191, v18, s[8:9]
	global_load_dword v161, v18, s[8:9] offset:64
	global_load_dword v193, v18, s[8:9] offset:128
	global_load_dword v190, v18, s[8:9] offset:192
	global_load_dword v195, v18, s[8:9] offset:256
	global_load_dword v192, v18, s[8:9] offset:320
	global_load_dword v196, v18, s[8:9] offset:384
	global_load_dword v194, v18, s[8:9] offset:448
	s_add_u32 s8, s18, s2
	s_mov_b64 s[22:23], s[30:31]
	s_addc_u32 s9, s19, 0
	s_lshl_b32 s2, s0, 7
	s_add_u32 s10, s22, s2
	s_movk_i32 s2, 0x210
	v_mul_lo_u32 v102, v144, s2
	v_add3_u32 v163, 0, v102, v153
	s_addc_u32 s11, s23, 0
	global_load_dwordx4 v[18:21], v78, s[8:9]
	global_load_dwordx4 v[22:25], v78, s[10:11]
	global_load_dwordx4 v[26:29], v78, s[10:11] offset:64
	v_readlane_b32 s36, v249, 0
	s_and_b32 s36, s36, 63
	s_lshl_b32 s36, s36, 9
	s_add_u32 s36, s36, 0x2308000
	s_add_u32 s36, s94, s36
	s_addc_u32 s37, s95, 0
	s_add_u32 s38, s36, 0x8000
	s_addc_u32 s39, s37, 0
	v_lshlrev_b32_e32 v238, 3, v162
	s_nop 1
	global_load_dwordx2 v[234:235], v238, s[36:37]
	global_load_dwordx2 v[236:237], v238, s[38:39]
	s_waitcnt lgkmcnt(0)
	s_barrier
; #define LAS __attribute__((address_space(3)))
; #define S5_UPDATE(K, hre, him, xq) do { const v2u xb_ = (xq); \
;     _Pragma("unroll") for (int j = 0; j < 4; ++j) { const f32x4 cre_ = K.ar[j] * hre[j] - K.ai[j] * him[j], cim_ = K.ar[j] * him[j] + K.ai[j] * hre[j]; \
;         hre[j] = MFMA16K16(K.Bf[2 * j], xb_, cre_); him[j] = MFMA16K16(K.Bf[2 * j + 1], xb_, cim_); } } while (0)
; __device__ __forceinline__ void s5_prompt_task(const Args& a, const Ctx& C, int b, int g, v4u (&xv)[8]) {
;     ...
;     const int chunk = 16 * w + n;
;     f32x4 hre[4], him[4];
; #pragma unroll
;     for (int j = 0; j < 4; ++j) { hre[j] = (f32x4){0.f, 0.f, 0.f, 0.f}; him[j] = (f32x4){0.f, 0.f, 0.f, 0.f}; }
;     const LAS unsigned char* xsl = XS + chunk * 528 + q * 8;
;     for (int t = 0; t < 16; ++t) { const v2u xq = *(const LAS v2u*)(xsl + t * 32); S5_UPDATE(K, hre, him, xq); }
	ds_read2_b64 v[104:107], v163 offset1:4
	s_waitcnt vmcnt(32)
	v_mov_b32_e32 v78, v30
	v_mov_b32_e32 v79, v32
	v_mov_b32_e32 v80, v2
	v_mov_b32_e32 v81, v4
	v_pk_mul_f32 v[86:87], v[78:79], 0 op_sel_hi:[1,0]
	v_pk_mul_f32 v[90:91], v[80:81], 0 op_sel_hi:[1,0]
	v_xor_b32_e32 v83, 0x80000000, v33
	v_xor_b32_e32 v82, 0x80000000, v31
	v_xor_b32_e32 v85, 0x80000000, v5
	v_xor_b32_e32 v84, 0x80000000, v3
	v_mov_b32_e32 v118, v3
	v_pk_fma_f32 v[82:83], v[82:83], 0, v[86:87] op_sel_hi:[1,0,1]
	v_pk_fma_f32 v[84:85], v[84:85], 0, v[90:91] op_sel_hi:[1,0,1]
	v_mov_b32_e32 v88, v31
	v_mov_b32_e32 v89, v33
	v_mov_b32_e32 v119, v5
	s_waitcnt vmcnt(31) lgkmcnt(0)
	v_mfma_f32_16x16x16_bf16 v[138:141], v[114:115], v[104:105], v[82:85]
	s_nop 2
	v_fma_f32 v82, v88, 0, v86
	v_fma_f32 v83, v89, 0, v87
	v_pk_fma_f32 v[84:85], v[118:119], 0, v[90:91] op_sel_hi:[1,0,1]
	v_mov_b32_e32 v86, v6
	v_mov_b32_e32 v87, v8
	s_waitcnt vmcnt(30)
	v_mfma_f32_16x16x16_bf16 v[146:149], v[116:117], v[104:105], v[82:85]
	v_mul_f32_e64 v94, v86, 0
	v_mul_f32_e64 v95, v87, 0
	v_xor_b32_e32 v91, 0x80000000, v9
	v_xor_b32_e32 v90, 0x80000000, v7
	s_waitcnt vmcnt(29)
	v_mov_b32_e32 v82, v70
	v_mov_b32_e32 v83, v72
	v_mov_b32_e32 v120, v7
	v_pk_mul_f32 v[84:85], v[82:83], 0 op_sel_hi:[1,0]
	v_pk_fma_f32 v[92:93], v[90:91], 0, v[94:95] op_sel_hi:[1,0,1]
	v_xor_b32_e32 v91, 0x80000000, v73
	v_xor_b32_e32 v90, 0x80000000, v71
	v_mov_b32_e32 v121, v9
	v_pk_fma_f32 v[90:91], v[90:91], 0, v[84:85] op_sel_hi:[1,0,1]
	v_pk_fma_f32 v[98:99], v[120:121], 0, v[94:95] op_sel_hi:[1,0,1]
	v_mov_b32_e32 v94, v71
	v_mov_b32_e32 v95, v73
	s_waitcnt vmcnt(26)
	v_mfma_f32_16x16x16_bf16 v[150:153], v[126:127], v[104:105], v[90:93]
	v_fma_f32 v96, v94, 0, v84
	v_fma_f32 v97, v95, 0, v85
	v_mov_b32_e32 v84, v74
	v_mov_b32_e32 v85, v76
	v_mov_b32_e32 v92, v10
	v_mov_b32_e32 v93, v12
	s_waitcnt vmcnt(25)
	v_mfma_f32_16x16x16_bf16 v[154:157], v[128:129], v[104:105], v[96:99]
	v_mul_f32_e64 v100, v92, 0
	v_mul_f32_e64 v101, v93, 0
	v_pk_mul_f32 v[90:91], v[84:85], 0 op_sel_hi:[1,0]
	v_mov_b32_e32 v122, v11
	v_xor_b32_e32 v97, 0x80000000, v13
	v_xor_b32_e32 v96, 0x80000000, v11
	v_pk_fma_f32 v[98:99], v[96:97], 0, v[100:101] op_sel_hi:[1,0,1]
	v_xor_b32_e32 v97, 0x80000000, v77
	v_xor_b32_e32 v96, 0x80000000, v75
	v_pk_fma_f32 v[96:97], v[96:97], 0, v[90:91] op_sel_hi:[1,0,1]
	v_mov_b32_e32 v123, v13
	v_pk_fma_f32 v[166:167], v[122:123], 0, v[100:101] op_sel_hi:[1,0,1]
	s_waitcnt vmcnt(24)
	v_mfma_f32_16x16x16_bf16 v[168:171], v[130:131], v[104:105], v[96:99]
	v_xor_b32_e32 v143, 0x80000000, v17
	v_xor_b32_e32 v142, 0x80000000, v15
	v_mov_b32_e32 v124, v15
	v_mov_b32_e32 v98, v75
	v_mov_b32_e32 v99, v77
	v_mov_b32_e32 v96, v14
	v_mov_b32_e32 v97, v16
	v_pk_fma_f32 v[164:165], v[98:99], 0, v[90:91] op_sel_hi:[1,0,1]
	v_mov_b32_e32 v90, v66
	v_mov_b32_e32 v91, v68
	v_pk_mul_f32 v[100:101], v[96:97], 0 op_sel_hi:[1,0]
	v_pk_mul_f32 v[108:109], v[90:91], 0 op_sel_hi:[1,0]
	v_pk_fma_f32 v[174:175], v[142:143], 0, v[100:101] op_sel_hi:[1,0,1]
	v_xor_b32_e32 v143, 0x80000000, v69
	v_xor_b32_e32 v142, 0x80000000, v67
	v_mov_b32_e32 v125, v17
	v_pk_fma_f32 v[172:173], v[142:143], 0, v[108:109] op_sel_hi:[1,0,1]
	v_pk_fma_f32 v[176:177], v[124:125], 0, v[100:101] op_sel_hi:[1,0,1]
	v_mov_b32_e32 v100, v67
	v_mov_b32_e32 v101, v69
	s_waitcnt vmcnt(22)
	v_mfma_f32_16x16x16_bf16 v[178:181], v[134:135], v[104:105], v[172:175]
	s_add_i32 s8, 0, 0x10800
	v_add_u32_e32 v3, s8, v102
	v_lshlrev_b32_e32 v7, 5, v145
	v_pk_fma_f32 v[174:175], v[100:101], 0, v[108:109] op_sel_hi:[1,0,1]
	v_mfma_f32_16x16x16_bf16 v[164:167], v[132:133], v[104:105], v[164:167]
	v_mul_f32_e64 v108, v88, v146
	v_mul_f32_e64 v109, v89, v147
	v_add_u32_e32 v3, v3, v7
	v_pk_fma_f32 v[182:183], v[78:79], v[138:139], v[108:109] neg_lo:[0,0,1] neg_hi:[0,0,1]
	s_waitcnt vmcnt(21)
	v_mfma_f32_16x16x16_bf16 v[172:175], v[136:137], v[104:105], v[174:177]
	v_mul_f32_e64 v104, v118, v148
	v_mul_f32_e64 v105, v119, v149
	v_pk_mul_f32 v[108:109], v[78:79], v[146:147]
	v_pk_fma_f32 v[184:185], v[80:81], v[140:141], v[104:105] neg_lo:[0,0,1] neg_hi:[0,0,1]
	v_pk_mul_f32 v[104:105], v[80:81], v[148:149]
	v_pk_fma_f32 v[138:139], v[88:89], v[138:139], v[108:109]
	v_pk_fma_f32 v[140:141], v[118:119], v[140:141], v[104:105]
	v_pk_mul_f32 v[104:105], v[120:121], v[156:157]
	v_pk_mul_f32 v[108:109], v[94:95], v[154:155]
	v_pk_fma_f32 v[148:149], v[86:87], v[152:153], v[104:105] neg_lo:[0,0,1] neg_hi:[0,0,1]
	v_pk_fma_f32 v[146:147], v[82:83], v[150:151], v[108:109] neg_lo:[0,0,1] neg_hi:[0,0,1]
	v_pk_mul_f32 v[104:105], v[86:87], v[156:157]
	v_pk_mul_f32 v[108:109], v[82:83], v[154:155]
	v_pk_fma_f32 v[152:153], v[120:121], v[152:153], v[104:105]
	v_pk_fma_f32 v[150:151], v[94:95], v[150:151], v[108:109]
	v_pk_mul_f32 v[104:105], v[122:123], v[166:167]
	v_pk_mul_f32 v[108:109], v[98:99], v[164:165]
	v_pk_fma_f32 v[156:157], v[92:93], v[170:171], v[104:105] neg_lo:[0,0,1] neg_hi:[0,0,1]
	v_pk_fma_f32 v[154:155], v[84:85], v[168:169], v[108:109] neg_lo:[0,0,1] neg_hi:[0,0,1]
	v_pk_mul_f32 v[104:105], v[92:93], v[166:167]
	v_pk_mul_f32 v[108:109], v[84:85], v[164:165]
	v_pk_fma_f32 v[166:167], v[122:123], v[170:171], v[104:105]
	v_pk_fma_f32 v[164:165], v[98:99], v[168:169], v[108:109]
	v_pk_mul_f32 v[104:105], v[124:125], v[174:175]
	v_pk_mul_f32 v[108:109], v[100:101], v[172:173]
	v_pk_fma_f32 v[170:171], v[96:97], v[180:181], v[104:105] neg_lo:[0,0,1] neg_hi:[0,0,1]
	v_pk_fma_f32 v[168:169], v[90:91], v[178:179], v[108:109] neg_lo:[0,0,1] neg_hi:[0,0,1]
	v_pk_mul_f32 v[104:105], v[96:97], v[174:175]
	v_pk_mul_f32 v[108:109], v[90:91], v[172:173]
	v_mfma_f32_16x16x16_bf16 v[138:141], v[116:117], v[106:107], v[138:141]
	v_fma_f32 v174, v124, v180, v104
	v_fma_f32 v175, v125, v181, v105
	v_pk_fma_f32 v[172:173], v[100:101], v[178:179], v[108:109]
	s_add_u32 s4, s94, s4
	v_mfma_f32_16x16x16_bf16 v[182:185], v[114:115], v[106:107], v[182:185]
	s_addc_u32 s5, s95, s5
	s_nop 1
	v_pk_mul_f32 v[108:109], v[118:119], v[140:141]
	v_pk_mul_f32 v[142:143], v[88:89], v[138:139]
	v_mfma_f32_16x16x16_bf16 v[146:149], v[126:127], v[106:107], v[146:149]
	v_mul_f32_e64 v138, v78, v138
	v_mul_f32_e64 v139, v79, v139
	v_pk_fma_f32 v[178:179], v[80:81], v[184:185], v[108:109] neg_lo:[0,0,1] neg_hi:[0,0,1]
	v_pk_fma_f32 v[176:177], v[78:79], v[182:183], v[142:143] neg_lo:[0,0,1] neg_hi:[0,0,1]
	v_mfma_f32_16x16x16_bf16 v[150:153], v[128:129], v[106:107], v[150:153]
	v_mul_f32_e64 v108, v80, v140
	v_mul_f32_e64 v109, v81, v141
	v_lshlrev_b32_e32 v7, 4, v144
	s_mov_b32 s2, 0x2308000
	v_mfma_f32_16x16x16_bf16 v[154:157], v[130:131], v[106:107], v[154:157]
	v_mov_b32_e32 v160, v111
	v_mfma_f32_16x16x16_bf16 v[164:167], v[132:133], v[106:107], v[164:167]
	v_mfma_f32_16x16x16_bf16 v[168:171], v[134:135], v[106:107], v[168:171]
	v_mfma_f32_16x16x16_bf16 v[104:107], v[136:137], v[106:107], v[172:175]
	s_nop 2
	ds_read2_b64 v[172:175], v163 offset0:8 offset1:12
	s_waitcnt lgkmcnt(0)
; #define LAS __attribute__((address_space(3)))
; #define S5_UPDATE(K, hre, him, xq) do { const v2u xb_ = (xq); \
;     _Pragma("unroll") for (int j = 0; j < 4; ++j) { const f32x4 cre_ = K.ar[j] * hre[j] - K.ai[j] * him[j], cim_ = K.ar[j] * him[j] + K.ai[j] * hre[j]; \
;         hre[j] = MFMA16K16(K.Bf[2 * j], xb_, cre_); him[j] = MFMA16K16(K.Bf[2 * j + 1], xb_, cim_); } } while (0)
; __device__ __forceinline__ void s5_prompt_task(const Args& a, const Ctx& C, int b, int g, v4u (&xv)[8]) {
;     ...
;     for (int t = 0; t < 16; ++t) { const v2u xq = *(const LAS v2u*)(xsl + t * 32); S5_UPDATE(K, hre, him, xq); }
	v_mfma_f32_16x16x16_bf16 v[140:143], v[114:115], v[172:173], v[176:179]
	s_nop 2
	v_fma_f32 v178, v118, v184, v108
	v_fma_f32 v179, v119, v185, v109
	v_pk_fma_f32 v[176:177], v[88:89], v[182:183], v[138:139]
	v_pk_mul_f32 v[108:109], v[120:121], v[152:153]
	v_pk_mul_f32 v[138:139], v[94:95], v[150:151]
	v_pk_fma_f32 v[182:183], v[86:87], v[148:149], v[108:109] neg_lo:[0,0,1] neg_hi:[0,0,1]
	v_pk_fma_f32 v[180:181], v[82:83], v[146:147], v[138:139] neg_lo:[0,0,1] neg_hi:[0,0,1]
	v_pk_mul_f32 v[108:109], v[86:87], v[152:153]
	v_pk_mul_f32 v[138:139], v[82:83], v[150:151]
	v_mfma_f32_16x16x16_bf16 v[176:179], v[116:117], v[172:173], v[176:179]
	v_fma_f32 v148, v120, v148, v108
	v_fma_f32 v149, v121, v149, v109
	v_pk_fma_f32 v[146:147], v[94:95], v[146:147], v[138:139]
	v_pk_mul_f32 v[108:109], v[122:123], v[166:167]
	v_pk_mul_f32 v[138:139], v[98:99], v[164:165]
	v_pk_fma_f32 v[152:153], v[92:93], v[156:157], v[108:109] neg_lo:[0,0,1] neg_hi:[0,0,1]
	v_pk_fma_f32 v[150:151], v[84:85], v[154:155], v[138:139] neg_lo:[0,0,1] neg_hi:[0,0,1]
	v_pk_mul_f32 v[108:109], v[92:93], v[166:167]
	v_pk_mul_f32 v[138:139], v[84:85], v[164:165]
	v_pk_fma_f32 v[156:157], v[122:123], v[156:157], v[108:109]
	v_pk_fma_f32 v[154:155], v[98:99], v[154:155], v[138:139]
	v_pk_mul_f32 v[108:109], v[124:125], v[106:107]
	v_pk_mul_f32 v[138:139], v[100:101], v[104:105]
	v_mfma_f32_16x16x16_bf16 v[146:149], v[128:129], v[172:173], v[146:149]
	v_fma_f32 v166, v96, v170, -v108
	v_fma_f32 v167, v97, v171, -v109
	v_pk_fma_f32 v[164:165], v[90:91], v[168:169], v[138:139] neg_lo:[0,0,1] neg_hi:[0,0,1]
	v_pk_mul_f32 v[138:139], v[96:97], v[106:107]
	v_pk_mul_f32 v[104:105], v[90:91], v[104:105]
	v_mfma_f32_16x16x16_bf16 v[180:183], v[126:127], v[172:173], v[180:183]
	v_mfma_f32_16x16x16_bf16 v[106:109], v[134:135], v[172:173], v[164:167]
	s_nop 2
	v_fma_f32 v166, v124, v170, v138
	v_fma_f32 v167, v125, v171, v139
	v_pk_fma_f32 v[164:165], v[100:101], v[168:169], v[104:105]
	v_pk_mul_f32 v[104:105], v[118:119], v[178:179]
	v_pk_mul_f32 v[138:139], v[88:89], v[176:177]
	v_mfma_f32_16x16x16_bf16 v[154:157], v[132:133], v[172:173], v[154:157]
	v_fma_f32 v170, v80, v142, -v104
	v_fma_f32 v171, v81, v143, -v105
	v_pk_fma_f32 v[168:169], v[78:79], v[140:141], v[138:139] neg_lo:[0,0,1] neg_hi:[0,0,1]
	v_pk_mul_f32 v[104:105], v[80:81], v[178:179]
	v_pk_mul_f32 v[138:139], v[78:79], v[176:177]
	v_mfma_f32_16x16x16_bf16 v[150:153], v[130:131], v[172:173], v[150:153]
	v_fma_f32 v142, v118, v142, v104
	v_fma_f32 v143, v119, v143, v105
	v_pk_fma_f32 v[140:141], v[88:89], v[140:141], v[138:139]
	v_pk_mul_f32 v[104:105], v[120:121], v[148:149]
	v_mfma_f32_16x16x16_bf16 v[164:167], v[136:137], v[172:173], v[164:167]
	v_fma_f32 v178, v86, v182, -v104
	v_fma_f32 v179, v87, v183, -v105
	v_pk_mul_f32 v[104:105], v[86:87], v[148:149]
	v_mfma_f32_16x16x16_bf16 v[138:141], v[116:117], v[174:175], v[140:143]
	v_fma_f32 v148, v120, v182, v104
	v_fma_f32 v149, v121, v183, v105
	v_pk_mul_f32 v[104:105], v[122:123], v[156:157]
	v_pk_mul_f32 v[142:143], v[94:95], v[146:147]
	v_pk_fma_f32 v[182:183], v[92:93], v[152:153], v[104:105] neg_lo:[0,0,1] neg_hi:[0,0,1]
	v_pk_fma_f32 v[176:177], v[82:83], v[180:181], v[142:143] neg_lo:[0,0,1] neg_hi:[0,0,1]
	v_pk_mul_f32 v[142:143], v[82:83], v[146:147]
	v_pk_mul_f32 v[104:105], v[92:93], v[156:157]
	v_pk_fma_f32 v[146:147], v[94:95], v[180:181], v[142:143]
	v_pk_mul_f32 v[142:143], v[98:99], v[154:155]
	v_mfma_f32_16x16x16_bf16 v[168:171], v[114:115], v[174:175], v[168:171]
	v_fma_f32 v180, v84, v150, -v142
	v_fma_f32 v181, v85, v151, -v143
	v_pk_mul_f32 v[142:143], v[84:85], v[154:155]
	v_pk_fma_f32 v[152:153], v[122:123], v[152:153], v[104:105]
	v_pk_fma_f32 v[150:151], v[98:99], v[150:151], v[142:143]
	v_pk_mul_f32 v[104:105], v[124:125], v[166:167]
	v_pk_mul_f32 v[142:143], v[100:101], v[164:165]
	v_mfma_f32_16x16x16_bf16 v[146:149], v[128:129], v[174:175], v[146:149]
	v_mfma_f32_16x16x16_bf16 v[156:159], v[130:131], v[174:175], v[180:183]
	s_nop 2
	v_fma_f32 v182, v96, v108, -v104
	v_fma_f32 v183, v97, v109, -v105
	v_pk_fma_f32 v[180:181], v[90:91], v[106:107], v[142:143] neg_lo:[0,0,1] neg_hi:[0,0,1]
	v_pk_mul_f32 v[104:105], v[96:97], v[166:167]
	v_pk_mul_f32 v[142:143], v[90:91], v[164:165]
	ds_read2_b64 v[164:167], v163 offset0:16 offset1:20
	v_mfma_f32_16x16x16_bf16 v[176:179], v[126:127], v[174:175], v[176:179]
	v_fma_f32 v108, v124, v108, v104
	v_fma_f32 v109, v125, v109, v105
	v_pk_fma_f32 v[106:107], v[100:101], v[106:107], v[142:143]
	v_pk_mul_f32 v[142:143], v[88:89], v[138:139]
	v_mfma_f32_16x16x16_bf16 v[150:153], v[132:133], v[174:175], v[150:153]
	v_mul_f32_e64 v138, v78, v138
	v_mul_f32_e64 v139, v79, v139
	v_pk_fma_f32 v[172:173], v[78:79], v[168:169], v[142:143] neg_lo:[0,0,1] neg_hi:[0,0,1]
	v_pk_fma_f32 v[168:169], v[88:89], v[168:169], v[138:139]
	v_mfma_f32_16x16x16_bf16 v[104:107], v[136:137], v[174:175], v[106:109]
	v_mul_f32_e64 v138, v94, v146
	v_mul_f32_e64 v139, v95, v147
	s_nop 0
	v_pk_mul_f32 v[108:109], v[118:119], v[140:141]
	v_mfma_f32_16x16x16_bf16 v[180:183], v[134:135], v[174:175], v[180:183]
	v_fma_f32 v174, v80, v170, -v108
	v_fma_f32 v175, v81, v171, -v109
	v_pk_mul_f32 v[108:109], v[80:81], v[140:141]
	s_nop 0
	v_pk_fma_f32 v[170:171], v[118:119], v[170:171], v[108:109]
	v_pk_mul_f32 v[108:109], v[120:121], v[148:149]
	s_waitcnt lgkmcnt(0)
; #define LAS __attribute__((address_space(3)))
; #define S5_UPDATE(K, hre, him, xq) do { const v2u xb_ = (xq); \
;     _Pragma("unroll") for (int j = 0; j < 4; ++j) { const f32x4 cre_ = K.ar[j] * hre[j] - K.ai[j] * him[j], cim_ = K.ar[j] * him[j] + K.ai[j] * hre[j]; \
;         hre[j] = MFMA16K16(K.Bf[2 * j], xb_, cre_); him[j] = MFMA16K16(K.Bf[2 * j + 1], xb_, cim_); } } while (0)
; __device__ __forceinline__ void s5_prompt_task(const Args& a, const Ctx& C, int b, int g, v4u (&xv)[8]) {
;     ...
;     for (int t = 0; t < 16; ++t) { const v2u xq = *(const LAS v2u*)(xsl + t * 32); S5_UPDATE(K, hre, him, xq); }
	v_mfma_f32_16x16x16_bf16 v[140:143], v[114:115], v[164:165], v[172:175]
	s_nop 2
	v_fma_f32 v174, v86, v178, -v108
	v_fma_f32 v175, v87, v179, -v109
	v_pk_fma_f32 v[172:173], v[82:83], v[176:177], v[138:139] neg_lo:[0,0,1] neg_hi:[0,0,1]
	v_pk_mul_f32 v[108:109], v[86:87], v[148:149]
	v_pk_mul_f32 v[138:139], v[82:83], v[146:147]
	v_mfma_f32_16x16x16_bf16 v[168:171], v[116:117], v[164:165], v[168:171]
	v_fma_f32 v148, v120, v178, v108
	v_fma_f32 v149, v121, v179, v109
	v_pk_fma_f32 v[146:147], v[94:95], v[176:177], v[138:139]
	v_pk_mul_f32 v[108:109], v[122:123], v[152:153]
	v_pk_mul_f32 v[138:139], v[98:99], v[150:151]
	v_pk_fma_f32 v[178:179], v[92:93], v[158:159], v[108:109] neg_lo:[0,0,1] neg_hi:[0,0,1]
	v_pk_fma_f32 v[176:177], v[84:85], v[156:157], v[138:139] neg_lo:[0,0,1] neg_hi:[0,0,1]
	v_pk_mul_f32 v[108:109], v[92:93], v[152:153]
	v_pk_mul_f32 v[138:139], v[84:85], v[150:151]
	v_pk_fma_f32 v[158:159], v[122:123], v[158:159], v[108:109]
	v_pk_fma_f32 v[156:157], v[98:99], v[156:157], v[138:139]
	v_pk_mul_f32 v[108:109], v[124:125], v[106:107]
	v_pk_mul_f32 v[138:139], v[100:101], v[104:105]
	v_mfma_f32_16x16x16_bf16 v[146:149], v[128:129], v[164:165], v[146:149]
	v_mul_f32_e64 v104, v90, v104
	v_mul_f32_e64 v105, v91, v105
	v_mfma_f32_16x16x16_bf16 v[152:155], v[130:131], v[164:165], v[176:179]
	s_nop 2
	v_fma_f32 v178, v96, v182, -v108
	v_fma_f32 v179, v97, v183, -v109
	v_pk_fma_f32 v[176:177], v[90:91], v[180:181], v[138:139] neg_lo:[0,0,1] neg_hi:[0,0,1]
	v_pk_mul_f32 v[138:139], v[96:97], v[106:107]
	v_mfma_f32_16x16x16_bf16 v[172:175], v[126:127], v[164:165], v[172:175]
	v_mfma_f32_16x16x16_bf16 v[106:109], v[134:135], v[164:165], v[176:179]
	s_nop 2
	v_fma_f32 v178, v124, v182, v138
	v_fma_f32 v179, v125, v183, v139
	v_pk_fma_f32 v[176:177], v[100:101], v[180:181], v[104:105]
	v_pk_mul_f32 v[104:105], v[118:119], v[170:171]
	v_pk_mul_f32 v[138:139], v[88:89], v[168:169]
	v_mfma_f32_16x16x16_bf16 v[156:159], v[132:133], v[164:165], v[156:159]
	v_fma_f32 v182, v80, v142, -v104
	v_fma_f32 v183, v81, v143, -v105
	v_pk_fma_f32 v[180:181], v[78:79], v[140:141], v[138:139] neg_lo:[0,0,1] neg_hi:[0,0,1]
	v_pk_mul_f32 v[104:105], v[80:81], v[170:171]
	v_pk_mul_f32 v[138:139], v[78:79], v[168:169]
	v_pk_fma_f32 v[142:143], v[118:119], v[142:143], v[104:105]
	v_pk_fma_f32 v[140:141], v[88:89], v[140:141], v[138:139]
	v_mfma_f32_16x16x16_bf16 v[176:179], v[136:137], v[164:165], v[176:179]
	v_mul_f32_e64 v104, v120, v148
	v_mul_f32_e64 v105, v121, v149
	v_pk_fma_f32 v[170:171], v[86:87], v[174:175], v[104:105] neg_lo:[0,0,1] neg_hi:[0,0,1]
	v_mfma_f32_16x16x16_bf16 v[138:141], v[116:117], v[166:167], v[140:143]
	v_mul_f32_e64 v104, v86, v148
	v_mul_f32_e64 v105, v87, v149
	s_nop 0
	v_pk_mul_f32 v[142:143], v[94:95], v[146:147]
	v_mfma_f32_16x16x16_bf16 v[180:183], v[114:115], v[166:167], v[180:183]
	v_fma_f32 v168, v82, v172, -v142
	v_fma_f32 v169, v83, v173, -v143
	v_pk_mul_f32 v[142:143], v[82:83], v[146:147]
	s_nop 0
	v_mfma_f32_16x16x16_bf16 v[148:151], v[126:127], v[166:167], v[168:171]
	s_nop 2
	v_fma_f32 v170, v120, v174, v104
	v_fma_f32 v171, v121, v175, v105
	v_pk_fma_f32 v[168:169], v[94:95], v[172:173], v[142:143]
	v_pk_mul_f32 v[104:105], v[122:123], v[158:159]
	v_pk_mul_f32 v[142:143], v[98:99], v[156:157]
	v_pk_fma_f32 v[174:175], v[92:93], v[154:155], v[104:105] neg_lo:[0,0,1] neg_hi:[0,0,1]
	v_pk_fma_f32 v[172:173], v[84:85], v[152:153], v[142:143] neg_lo:[0,0,1] neg_hi:[0,0,1]
	v_pk_mul_f32 v[104:105], v[92:93], v[158:159]
	v_pk_mul_f32 v[142:143], v[84:85], v[156:157]
	v_pk_fma_f32 v[154:155], v[122:123], v[154:155], v[104:105]
	v_pk_fma_f32 v[152:153], v[98:99], v[152:153], v[142:143]
	v_pk_mul_f32 v[104:105], v[124:125], v[178:179]
	v_pk_mul_f32 v[142:143], v[100:101], v[176:177]
	v_pk_fma_f32 v[158:159], v[96:97], v[108:109], v[104:105] neg_lo:[0,0,1] neg_hi:[0,0,1]
	v_pk_fma_f32 v[156:157], v[90:91], v[106:107], v[142:143] neg_lo:[0,0,1] neg_hi:[0,0,1]
	v_pk_mul_f32 v[104:105], v[96:97], v[178:179]
	v_pk_mul_f32 v[142:143], v[90:91], v[176:177]
	v_pk_fma_f32 v[108:109], v[124:125], v[108:109], v[104:105]
	v_pk_fma_f32 v[106:107], v[100:101], v[106:107], v[142:143]
	v_mfma_f32_16x16x16_bf16 v[168:171], v[128:129], v[166:167], v[168:171]
	v_mul_f32_e64 v142, v88, v138
	v_mul_f32_e64 v143, v89, v139
	v_pk_mul_f32 v[138:139], v[78:79], v[138:139]
	v_pk_fma_f32 v[176:177], v[78:79], v[180:181], v[142:143] neg_lo:[0,0,1] neg_hi:[0,0,1]
	v_mfma_f32_16x16x16_bf16 v[172:175], v[130:131], v[166:167], v[172:175]
	v_mfma_f32_16x16x16_bf16 v[152:155], v[132:133], v[166:167], v[152:155]
	v_mfma_f32_16x16x16_bf16 v[156:159], v[134:135], v[166:167], v[156:159]
	v_mfma_f32_16x16x16_bf16 v[104:107], v[136:137], v[166:167], v[106:109]
	ds_read2_b64 v[164:167], v163 offset0:24 offset1:28
	s_nop 1
	v_pk_mul_f32 v[108:109], v[118:119], v[140:141]
	s_nop 0
	v_pk_fma_f32 v[178:179], v[80:81], v[182:183], v[108:109] neg_lo:[0,0,1] neg_hi:[0,0,1]
	v_pk_mul_f32 v[108:109], v[80:81], v[140:141]
	s_waitcnt lgkmcnt(0)
; #define LAS __attribute__((address_space(3)))
; #define S5_UPDATE(K, hre, him, xq) do { const v2u xb_ = (xq); \
;     _Pragma("unroll") for (int j = 0; j < 4; ++j) { const f32x4 cre_ = K.ar[j] * hre[j] - K.ai[j] * him[j], cim_ = K.ar[j] * him[j] + K.ai[j] * hre[j]; \
;         hre[j] = MFMA16K16(K.Bf[2 * j], xb_, cre_); him[j] = MFMA16K16(K.Bf[2 * j + 1], xb_, cim_); } } while (0)
; __device__ __forceinline__ void s5_prompt_task(const Args& a, const Ctx& C, int b, int g, v4u (&xv)[8]) {
;     ...
;     for (int t = 0; t < 16; ++t) { const v2u xq = *(const LAS v2u*)(xsl + t * 32); S5_UPDATE(K, hre, him, xq); }
	v_mfma_f32_16x16x16_bf16 v[140:143], v[114:115], v[164:165], v[176:179]
	s_nop 2
	v_fma_f32 v176, v88, v180, v138
	v_fma_f32 v177, v89, v181, v139
	v_pk_mul_f32 v[138:139], v[94:95], v[168:169]
	v_pk_fma_f32 v[178:179], v[118:119], v[182:183], v[108:109]
	v_pk_mul_f32 v[108:109], v[120:121], v[170:171]
	v_pk_fma_f32 v[180:181], v[82:83], v[148:149], v[138:139] neg_lo:[0,0,1] neg_hi:[0,0,1]
	v_pk_mul_f32 v[138:139], v[82:83], v[168:169]
	v_mfma_f32_16x16x16_bf16 v[176:179], v[116:117], v[164:165], v[176:179]
	v_fma_f32 v182, v86, v150, -v108
	v_fma_f32 v183, v87, v151, -v109
	v_pk_mul_f32 v[108:109], v[86:87], v[170:171]
	v_pk_fma_f32 v[148:149], v[94:95], v[148:149], v[138:139]
	v_pk_mul_f32 v[138:139], v[98:99], v[152:153]
	v_pk_fma_f32 v[150:151], v[120:121], v[150:151], v[108:109]
	v_pk_mul_f32 v[108:109], v[122:123], v[154:155]
	v_pk_fma_f32 v[168:169], v[84:85], v[172:173], v[138:139] neg_lo:[0,0,1] neg_hi:[0,0,1]
	v_pk_mul_f32 v[138:139], v[84:85], v[152:153]
	v_mfma_f32_16x16x16_bf16 v[146:149], v[128:129], v[164:165], v[148:151]
	v_fma_f32 v170, v92, v174, -v108
	v_fma_f32 v171, v93, v175, -v109
	v_pk_mul_f32 v[108:109], v[92:93], v[154:155]
	v_pk_fma_f32 v[150:151], v[98:99], v[172:173], v[138:139]
	v_pk_mul_f32 v[138:139], v[100:101], v[104:105]
	v_pk_fma_f32 v[152:153], v[122:123], v[174:175], v[108:109]
	v_pk_mul_f32 v[108:109], v[124:125], v[106:107]
	v_pk_fma_f32 v[172:173], v[90:91], v[156:157], v[138:139] neg_lo:[0,0,1] neg_hi:[0,0,1]
	v_pk_mul_f32 v[138:139], v[96:97], v[106:107]
	v_pk_mul_f32 v[104:105], v[90:91], v[104:105]
	v_mfma_f32_16x16x16_bf16 v[180:183], v[126:127], v[164:165], v[180:183]
	v_fma_f32 v174, v96, v158, -v108
	v_fma_f32 v175, v97, v159, -v109
	v_pk_fma_f32 v[158:159], v[124:125], v[158:159], v[138:139]
	v_pk_fma_f32 v[156:157], v[100:101], v[156:157], v[104:105]
	v_pk_mul_f32 v[104:105], v[118:119], v[178:179]
	v_pk_mul_f32 v[138:139], v[88:89], v[176:177]
	v_mfma_f32_16x16x16_bf16 v[150:153], v[132:133], v[164:165], v[150:153]
	v_mfma_f32_16x16x16_bf16 v[106:109], v[134:135], v[164:165], v[172:175]
	s_nop 2
	v_fma_f32 v174, v80, v142, -v104
	v_fma_f32 v175, v81, v143, -v105
	v_pk_fma_f32 v[172:173], v[78:79], v[140:141], v[138:139] neg_lo:[0,0,1] neg_hi:[0,0,1]
	v_pk_mul_f32 v[104:105], v[80:81], v[178:179]
	v_pk_mul_f32 v[138:139], v[78:79], v[176:177]
	v_mfma_f32_16x16x16_bf16 v[168:171], v[130:131], v[164:165], v[168:171]
	v_fma_f32 v142, v118, v142, v104
	v_fma_f32 v143, v119, v143, v105
	v_pk_fma_f32 v[140:141], v[88:89], v[140:141], v[138:139]
	v_pk_mul_f32 v[104:105], v[120:121], v[148:149]
	v_mfma_f32_16x16x16_bf16 v[154:157], v[136:137], v[164:165], v[156:159]
	v_fma_f32 v178, v86, v182, -v104
	v_fma_f32 v179, v87, v183, -v105
	v_pk_mul_f32 v[104:105], v[86:87], v[148:149]
	v_mfma_f32_16x16x16_bf16 v[138:141], v[116:117], v[166:167], v[140:143]
	v_fma_f32 v148, v120, v182, v104
	v_fma_f32 v149, v121, v183, v105
	v_pk_mul_f32 v[104:105], v[122:123], v[152:153]
	v_pk_mul_f32 v[142:143], v[94:95], v[146:147]
	v_pk_fma_f32 v[182:183], v[92:93], v[170:171], v[104:105] neg_lo:[0,0,1] neg_hi:[0,0,1]
	v_pk_fma_f32 v[176:177], v[82:83], v[180:181], v[142:143] neg_lo:[0,0,1] neg_hi:[0,0,1]
	v_pk_mul_f32 v[142:143], v[82:83], v[146:147]
	v_pk_mul_f32 v[104:105], v[92:93], v[152:153]
	v_pk_fma_f32 v[146:147], v[94:95], v[180:181], v[142:143]
	v_pk_mul_f32 v[142:143], v[98:99], v[150:151]
	v_pk_fma_f32 v[152:153], v[122:123], v[170:171], v[104:105]
	v_pk_fma_f32 v[180:181], v[84:85], v[168:169], v[142:143] neg_lo:[0,0,1] neg_hi:[0,0,1]
	v_pk_mul_f32 v[142:143], v[84:85], v[150:151]
	v_pk_mul_f32 v[104:105], v[124:125], v[156:157]
	v_pk_fma_f32 v[150:151], v[98:99], v[168:169], v[142:143]
	v_pk_mul_f32 v[142:143], v[100:101], v[154:155]
	v_pk_fma_f32 v[170:171], v[96:97], v[108:109], v[104:105] neg_lo:[0,0,1] neg_hi:[0,0,1]
	v_pk_fma_f32 v[168:169], v[90:91], v[106:107], v[142:143] neg_lo:[0,0,1] neg_hi:[0,0,1]
	v_pk_mul_f32 v[104:105], v[96:97], v[156:157]
	v_pk_mul_f32 v[142:143], v[90:91], v[154:155]
	v_pk_fma_f32 v[108:109], v[124:125], v[108:109], v[104:105]
	v_pk_fma_f32 v[106:107], v[100:101], v[106:107], v[142:143]
	v_mfma_f32_16x16x16_bf16 v[172:175], v[114:115], v[166:167], v[172:175]
	v_mul_f32_e64 v142, v88, v138
	v_mul_f32_e64 v143, v89, v139
	v_pk_mul_f32 v[138:139], v[78:79], v[138:139]
	v_mfma_f32_16x16x16_bf16 v[176:179], v[126:127], v[166:167], v[176:179]
	v_mfma_f32_16x16x16_bf16 v[146:149], v[128:129], v[166:167], v[146:149]
	v_mfma_f32_16x16x16_bf16 v[180:183], v[130:131], v[166:167], v[180:183]
	v_mfma_f32_16x16x16_bf16 v[150:153], v[132:133], v[166:167], v[150:153]
	v_mfma_f32_16x16x16_bf16 v[156:159], v[134:135], v[166:167], v[168:171]
	v_mfma_f32_16x16x16_bf16 v[104:107], v[136:137], v[166:167], v[106:109]
	ds_read2_b64 v[164:167], v163 offset0:32 offset1:36
	s_nop 0
	v_pk_fma_f32 v[168:169], v[78:79], v[172:173], v[142:143] neg_lo:[0,0,1] neg_hi:[0,0,1]
	v_pk_mul_f32 v[108:109], v[118:119], v[140:141]
	s_nop 0
	v_pk_fma_f32 v[170:171], v[80:81], v[174:175], v[108:109] neg_lo:[0,0,1] neg_hi:[0,0,1]
	v_pk_mul_f32 v[108:109], v[80:81], v[140:141]
	s_waitcnt lgkmcnt(0)
; #define LAS __attribute__((address_space(3)))
; #define S5_UPDATE(K, hre, him, xq) do { const v2u xb_ = (xq); \
;     _Pragma("unroll") for (int j = 0; j < 4; ++j) { const f32x4 cre_ = K.ar[j] * hre[j] - K.ai[j] * him[j], cim_ = K.ar[j] * him[j] + K.ai[j] * hre[j]; \
;         hre[j] = MFMA16K16(K.Bf[2 * j], xb_, cre_); him[j] = MFMA16K16(K.Bf[2 * j + 1], xb_, cim_); } } while (0)
; __device__ __forceinline__ void s5_prompt_task(const Args& a, const Ctx& C, int b, int g, v4u (&xv)[8]) {
;     ...
;     for (int t = 0; t < 16; ++t) { const v2u xq = *(const LAS v2u*)(xsl + t * 32); S5_UPDATE(K, hre, him, xq); }
	v_mfma_f32_16x16x16_bf16 v[140:143], v[114:115], v[164:165], v[168:171]
	s_nop 2
	v_fma_f32 v170, v118, v174, v108
	v_fma_f32 v171, v119, v175, v109
	v_pk_fma_f32 v[168:169], v[88:89], v[172:173], v[138:139]
	v_pk_mul_f32 v[108:109], v[120:121], v[148:149]
	v_pk_mul_f32 v[138:139], v[94:95], v[146:147]
	v_pk_fma_f32 v[174:175], v[86:87], v[178:179], v[108:109] neg_lo:[0,0,1] neg_hi:[0,0,1]
	v_pk_fma_f32 v[172:173], v[82:83], v[176:177], v[138:139] neg_lo:[0,0,1] neg_hi:[0,0,1]
	v_pk_mul_f32 v[108:109], v[86:87], v[148:149]
	v_pk_mul_f32 v[138:139], v[82:83], v[146:147]
	v_mfma_f32_16x16x16_bf16 v[168:171], v[116:117], v[164:165], v[168:171]
	v_fma_f32 v148, v120, v178, v108
	v_fma_f32 v149, v121, v179, v109
	v_pk_fma_f32 v[146:147], v[94:95], v[176:177], v[138:139]
	v_pk_mul_f32 v[108:109], v[122:123], v[152:153]
	v_pk_mul_f32 v[138:139], v[98:99], v[150:151]
	v_pk_fma_f32 v[178:179], v[92:93], v[182:183], v[108:109] neg_lo:[0,0,1] neg_hi:[0,0,1]
	v_pk_fma_f32 v[176:177], v[84:85], v[180:181], v[138:139] neg_lo:[0,0,1] neg_hi:[0,0,1]
	v_pk_mul_f32 v[138:139], v[84:85], v[150:151]
	v_pk_mul_f32 v[108:109], v[92:93], v[152:153]
	v_mfma_f32_16x16x16_bf16 v[152:155], v[130:131], v[164:165], v[176:179]
	s_nop 2
	v_fma_f32 v176, v98, v180, v138
	v_fma_f32 v177, v99, v181, v139
	v_pk_mul_f32 v[138:139], v[100:101], v[104:105]
	v_mfma_f32_16x16x16_bf16 v[146:149], v[128:129], v[164:165], v[146:149]
	v_fma_f32 v178, v122, v182, v108
	v_fma_f32 v179, v123, v183, v109
	v_pk_mul_f32 v[108:109], v[124:125], v[106:107]
	v_pk_fma_f32 v[180:181], v[90:91], v[156:157], v[138:139] neg_lo:[0,0,1] neg_hi:[0,0,1]
	v_pk_mul_f32 v[138:139], v[96:97], v[106:107]
	v_pk_mul_f32 v[104:105], v[90:91], v[104:105]
	v_mfma_f32_16x16x16_bf16 v[172:175], v[126:127], v[164:165], v[172:175]
	v_fma_f32 v182, v96, v158, -v108
	v_fma_f32 v183, v97, v159, -v109
	v_pk_fma_f32 v[158:159], v[124:125], v[158:159], v[138:139]
	v_pk_fma_f32 v[156:157], v[100:101], v[156:157], v[104:105]
	v_pk_mul_f32 v[104:105], v[118:119], v[170:171]
	v_pk_mul_f32 v[138:139], v[88:89], v[168:169]
	v_mfma_f32_16x16x16_bf16 v[176:179], v[132:133], v[164:165], v[176:179]
	v_mfma_f32_16x16x16_bf16 v[106:109], v[134:135], v[164:165], v[180:183]
	s_nop 2
	v_fma_f32 v182, v80, v142, -v104
	v_fma_f32 v183, v81, v143, -v105
	v_pk_fma_f32 v[180:181], v[78:79], v[140:141], v[138:139] neg_lo:[0,0,1] neg_hi:[0,0,1]
	v_pk_mul_f32 v[104:105], v[80:81], v[170:171]
	v_pk_mul_f32 v[138:139], v[78:79], v[168:169]
	v_pk_fma_f32 v[142:143], v[118:119], v[142:143], v[104:105]
	v_pk_fma_f32 v[140:141], v[88:89], v[140:141], v[138:139]
	v_mfma_f32_16x16x16_bf16 v[156:159], v[136:137], v[164:165], v[156:159]
	v_mul_f32_e64 v104, v120, v148
	v_mul_f32_e64 v105, v121, v149
	v_pk_fma_f32 v[170:171], v[86:87], v[174:175], v[104:105] neg_lo:[0,0,1] neg_hi:[0,0,1]
	v_mfma_f32_16x16x16_bf16 v[138:141], v[116:117], v[166:167], v[140:143]
	v_mul_f32_e64 v104, v86, v148
	v_mul_f32_e64 v105, v87, v149
	s_nop 0
	v_pk_mul_f32 v[142:143], v[94:95], v[146:147]
	v_mfma_f32_16x16x16_bf16 v[180:183], v[114:115], v[166:167], v[180:183]
	v_fma_f32 v168, v82, v172, -v142
	v_fma_f32 v169, v83, v173, -v143
	v_pk_mul_f32 v[142:143], v[82:83], v[146:147]
	s_nop 0
	v_mfma_f32_16x16x16_bf16 v[148:151], v[126:127], v[166:167], v[168:171]
	s_nop 2
	v_fma_f32 v170, v120, v174, v104
	v_fma_f32 v171, v121, v175, v105
	v_pk_fma_f32 v[168:169], v[94:95], v[172:173], v[142:143]
	v_pk_mul_f32 v[104:105], v[122:123], v[178:179]
	v_pk_mul_f32 v[142:143], v[98:99], v[176:177]
	v_pk_fma_f32 v[174:175], v[92:93], v[154:155], v[104:105] neg_lo:[0,0,1] neg_hi:[0,0,1]
	v_pk_fma_f32 v[172:173], v[84:85], v[152:153], v[142:143] neg_lo:[0,0,1] neg_hi:[0,0,1]
	v_pk_mul_f32 v[104:105], v[92:93], v[178:179]
	v_pk_mul_f32 v[142:143], v[84:85], v[176:177]
	v_pk_fma_f32 v[154:155], v[122:123], v[154:155], v[104:105]
	v_pk_fma_f32 v[152:153], v[98:99], v[152:153], v[142:143]
	v_pk_mul_f32 v[104:105], v[124:125], v[158:159]
	v_pk_mul_f32 v[142:143], v[100:101], v[156:157]
	v_pk_fma_f32 v[178:179], v[96:97], v[108:109], v[104:105] neg_lo:[0,0,1] neg_hi:[0,0,1]
	v_pk_fma_f32 v[176:177], v[90:91], v[106:107], v[142:143] neg_lo:[0,0,1] neg_hi:[0,0,1]
	v_pk_mul_f32 v[104:105], v[96:97], v[158:159]
	v_pk_mul_f32 v[142:143], v[90:91], v[156:157]
	ds_read2_b64 v[156:159], v163 offset0:40 offset1:44
	v_mfma_f32_16x16x16_bf16 v[168:171], v[128:129], v[166:167], v[168:171]
	v_fma_f32 v108, v124, v108, v104
	v_fma_f32 v109, v125, v109, v105
	v_pk_fma_f32 v[106:107], v[100:101], v[106:107], v[142:143]
	v_pk_mul_f32 v[142:143], v[88:89], v[138:139]
	v_mfma_f32_16x16x16_bf16 v[152:155], v[132:133], v[166:167], v[152:155]
	v_fma_f32 v164, v78, v180, -v142
	v_fma_f32 v165, v79, v181, -v143
	v_pk_mul_f32 v[138:139], v[78:79], v[138:139]
	v_mfma_f32_16x16x16_bf16 v[104:107], v[136:137], v[166:167], v[106:109]
	s_nop 2
	v_mul_f32_e64 v108, v118, v140
	v_mul_f32_e64 v109, v119, v141
	v_mfma_f32_16x16x16_bf16 v[172:175], v[130:131], v[166:167], v[172:175]
	v_mfma_f32_16x16x16_bf16 v[176:179], v[134:135], v[166:167], v[176:179]
	v_fma_f32 v166, v80, v182, -v108
	v_fma_f32 v167, v81, v183, -v109
	v_pk_mul_f32 v[108:109], v[80:81], v[140:141]
	s_waitcnt lgkmcnt(0)
; #define LAS __attribute__((address_space(3)))
; #define S5_UPDATE(K, hre, him, xq) do { const v2u xb_ = (xq); \
;     _Pragma("unroll") for (int j = 0; j < 4; ++j) { const f32x4 cre_ = K.ar[j] * hre[j] - K.ai[j] * him[j], cim_ = K.ar[j] * him[j] + K.ai[j] * hre[j]; \
;         hre[j] = MFMA16K16(K.Bf[2 * j], xb_, cre_); him[j] = MFMA16K16(K.Bf[2 * j + 1], xb_, cim_); } } while (0)
; __device__ __forceinline__ void s5_prompt_task(const Args& a, const Ctx& C, int b, int g, v4u (&xv)[8]) {
;     ...
;     for (int t = 0; t < 16; ++t) { const v2u xq = *(const LAS v2u*)(xsl + t * 32); S5_UPDATE(K, hre, him, xq); }
	v_mfma_f32_16x16x16_bf16 v[140:143], v[114:115], v[156:157], v[164:167]
	s_nop 2
	v_fma_f32 v166, v118, v182, v108
	v_fma_f32 v167, v119, v183, v109
	v_pk_fma_f32 v[164:165], v[88:89], v[180:181], v[138:139]
	v_pk_mul_f32 v[108:109], v[120:121], v[170:171]
	v_pk_mul_f32 v[138:139], v[94:95], v[168:169]
	v_pk_fma_f32 v[182:183], v[86:87], v[150:151], v[108:109] neg_lo:[0,0,1] neg_hi:[0,0,1]
	v_pk_fma_f32 v[180:181], v[82:83], v[148:149], v[138:139] neg_lo:[0,0,1] neg_hi:[0,0,1]
	v_pk_mul_f32 v[108:109], v[86:87], v[170:171]
	v_pk_mul_f32 v[138:139], v[82:83], v[168:169]
	v_mfma_f32_16x16x16_bf16 v[164:167], v[116:117], v[156:157], v[164:167]
	v_fma_f32 v150, v120, v150, v108
	v_fma_f32 v151, v121, v151, v109
	v_pk_fma_f32 v[148:149], v[94:95], v[148:149], v[138:139]
	v_pk_mul_f32 v[108:109], v[122:123], v[154:155]
	v_pk_mul_f32 v[138:139], v[98:99], v[152:153]
	v_pk_fma_f32 v[170:171], v[92:93], v[174:175], v[108:109] neg_lo:[0,0,1] neg_hi:[0,0,1]
	v_pk_fma_f32 v[168:169], v[84:85], v[172:173], v[138:139] neg_lo:[0,0,1] neg_hi:[0,0,1]
	v_pk_mul_f32 v[108:109], v[92:93], v[154:155]
	v_pk_mul_f32 v[138:139], v[84:85], v[152:153]
	v_mfma_f32_16x16x16_bf16 v[146:149], v[128:129], v[156:157], v[148:151]
	v_fma_f32 v152, v122, v174, v108
	v_fma_f32 v153, v123, v175, v109
	v_pk_mul_f32 v[108:109], v[124:125], v[106:107]
	v_pk_fma_f32 v[150:151], v[98:99], v[172:173], v[138:139]
	v_pk_mul_f32 v[138:139], v[100:101], v[104:105]
	v_pk_fma_f32 v[174:175], v[96:97], v[178:179], v[108:109] neg_lo:[0,0,1] neg_hi:[0,0,1]
	v_pk_fma_f32 v[172:173], v[90:91], v[176:177], v[138:139] neg_lo:[0,0,1] neg_hi:[0,0,1]
	v_pk_mul_f32 v[138:139], v[96:97], v[106:107]
	v_pk_mul_f32 v[104:105], v[90:91], v[104:105]
	v_mfma_f32_16x16x16_bf16 v[180:183], v[126:127], v[156:157], v[180:183]
	v_mfma_f32_16x16x16_bf16 v[106:109], v[134:135], v[156:157], v[172:175]
	s_nop 2
	v_fma_f32 v174, v124, v178, v138
	v_fma_f32 v175, v125, v179, v139
	v_pk_fma_f32 v[172:173], v[100:101], v[176:177], v[104:105]
	v_pk_mul_f32 v[104:105], v[118:119], v[166:167]
	v_pk_mul_f32 v[138:139], v[88:89], v[164:165]
	v_mfma_f32_16x16x16_bf16 v[168:171], v[130:131], v[156:157], v[168:171]
	v_mfma_f32_16x16x16_bf16 v[150:153], v[132:133], v[156:157], v[150:153]
	v_mfma_f32_16x16x16_bf16 v[154:157], v[136:137], v[156:157], v[172:175]
	s_nop 2
	v_fma_f32 v174, v80, v142, -v104
	v_fma_f32 v175, v81, v143, -v105
	v_pk_fma_f32 v[172:173], v[78:79], v[140:141], v[138:139] neg_lo:[0,0,1] neg_hi:[0,0,1]
	v_pk_mul_f32 v[104:105], v[80:81], v[166:167]
	v_pk_mul_f32 v[138:139], v[78:79], v[164:165]
	v_pk_fma_f32 v[142:143], v[118:119], v[142:143], v[104:105]
	v_pk_fma_f32 v[140:141], v[88:89], v[140:141], v[138:139]
	v_pk_mul_f32 v[104:105], v[120:121], v[148:149]
	v_mfma_f32_16x16x16_bf16 v[172:175], v[114:115], v[158:159], v[172:175]
	v_fma_f32 v166, v86, v182, -v104
	v_fma_f32 v167, v87, v183, -v105
	v_pk_mul_f32 v[104:105], v[86:87], v[148:149]
	v_mfma_f32_16x16x16_bf16 v[138:141], v[116:117], v[158:159], v[140:143]
	v_fma_f32 v148, v120, v182, v104
	v_fma_f32 v149, v121, v183, v105
	v_pk_mul_f32 v[104:105], v[122:123], v[152:153]
	v_pk_mul_f32 v[142:143], v[94:95], v[146:147]
	v_pk_fma_f32 v[178:179], v[92:93], v[170:171], v[104:105] neg_lo:[0,0,1] neg_hi:[0,0,1]
	v_pk_fma_f32 v[164:165], v[82:83], v[180:181], v[142:143] neg_lo:[0,0,1] neg_hi:[0,0,1]
	v_pk_mul_f32 v[142:143], v[82:83], v[146:147]
	v_pk_mul_f32 v[104:105], v[92:93], v[152:153]
	v_pk_fma_f32 v[146:147], v[94:95], v[180:181], v[142:143]
	v_pk_mul_f32 v[142:143], v[98:99], v[150:151]
	v_pk_fma_f32 v[152:153], v[122:123], v[170:171], v[104:105]
	v_pk_fma_f32 v[176:177], v[84:85], v[168:169], v[142:143] neg_lo:[0,0,1] neg_hi:[0,0,1]
	v_pk_mul_f32 v[142:143], v[84:85], v[150:151]
	v_pk_mul_f32 v[104:105], v[124:125], v[156:157]
	v_pk_fma_f32 v[150:151], v[98:99], v[168:169], v[142:143]
	v_pk_mul_f32 v[142:143], v[100:101], v[154:155]
	v_mfma_f32_16x16x16_bf16 v[146:149], v[128:129], v[158:159], v[146:149]
	v_fma_f32 v170, v96, v108, -v104
	v_fma_f32 v171, v97, v109, -v105
	v_pk_fma_f32 v[168:169], v[90:91], v[106:107], v[142:143] neg_lo:[0,0,1] neg_hi:[0,0,1]
	v_pk_mul_f32 v[104:105], v[96:97], v[156:157]
	v_pk_mul_f32 v[142:143], v[90:91], v[154:155]
	ds_read2_b64 v[154:157], v163 offset0:48 offset1:52
	v_mfma_f32_16x16x16_bf16 v[164:167], v[126:127], v[158:159], v[164:167]
	v_fma_f32 v108, v124, v108, v104
	v_fma_f32 v109, v125, v109, v105
	v_pk_fma_f32 v[106:107], v[100:101], v[106:107], v[142:143]
	v_pk_mul_f32 v[142:143], v[88:89], v[138:139]
	v_mfma_f32_16x16x16_bf16 v[150:153], v[132:133], v[158:159], v[150:153]
	v_mul_f32_e64 v138, v78, v138
	v_mul_f32_e64 v139, v79, v139
	v_pk_fma_f32 v[180:181], v[78:79], v[172:173], v[142:143] neg_lo:[0,0,1] neg_hi:[0,0,1]
	v_pk_fma_f32 v[172:173], v[88:89], v[172:173], v[138:139]
	v_mfma_f32_16x16x16_bf16 v[176:179], v[130:131], v[158:159], v[176:179]
	v_mul_f32_e64 v138, v94, v146
	v_mul_f32_e64 v139, v95, v147
	v_mfma_f32_16x16x16_bf16 v[104:107], v[136:137], v[158:159], v[106:109]
	s_nop 2
	v_mul_f32_e64 v108, v118, v140
	v_mul_f32_e64 v109, v119, v141
	v_mfma_f32_16x16x16_bf16 v[168:171], v[134:135], v[158:159], v[168:171]
	v_fma_f32 v182, v80, v174, -v108
	v_fma_f32 v183, v81, v175, -v109
	v_pk_mul_f32 v[108:109], v[80:81], v[140:141]
	s_waitcnt lgkmcnt(0)
; #define LAS __attribute__((address_space(3)))
; #define S5_UPDATE(K, hre, him, xq) do { const v2u xb_ = (xq); \
;     _Pragma("unroll") for (int j = 0; j < 4; ++j) { const f32x4 cre_ = K.ar[j] * hre[j] - K.ai[j] * him[j], cim_ = K.ar[j] * him[j] + K.ai[j] * hre[j]; \
;         hre[j] = MFMA16K16(K.Bf[2 * j], xb_, cre_); him[j] = MFMA16K16(K.Bf[2 * j + 1], xb_, cim_); } } while (0)
; __device__ __forceinline__ void s5_prompt_task(const Args& a, const Ctx& C, int b, int g, v4u (&xv)[8]) {
;     ...
;     for (int t = 0; t < 16; ++t) { const v2u xq = *(const LAS v2u*)(xsl + t * 32); S5_UPDATE(K, hre, him, xq); }
	v_mfma_f32_16x16x16_bf16 v[140:143], v[114:115], v[154:155], v[180:183]
	v_fma_f32 v174, v118, v174, v108
	v_fma_f32 v175, v119, v175, v109
	v_pk_mul_f32 v[108:109], v[120:121], v[148:149]
	v_pk_fma_f32 v[180:181], v[82:83], v[164:165], v[138:139] neg_lo:[0,0,1] neg_hi:[0,0,1]
	v_pk_mul_f32 v[138:139], v[82:83], v[146:147]
	v_mfma_f32_16x16x16_bf16 v[172:175], v[116:117], v[154:155], v[172:175]
	v_fma_f32 v182, v86, v166, -v108
	v_fma_f32 v183, v87, v167, -v109
	v_pk_mul_f32 v[108:109], v[86:87], v[148:149]
	v_pk_fma_f32 v[146:147], v[94:95], v[164:165], v[138:139]
	v_pk_mul_f32 v[138:139], v[98:99], v[150:151]
	v_pk_fma_f32 v[148:149], v[120:121], v[166:167], v[108:109]
	v_pk_mul_f32 v[108:109], v[122:123], v[152:153]
	v_pk_fma_f32 v[164:165], v[84:85], v[176:177], v[138:139] neg_lo:[0,0,1] neg_hi:[0,0,1]
	v_pk_mul_f32 v[138:139], v[84:85], v[150:151]
	v_pk_fma_f32 v[166:167], v[92:93], v[178:179], v[108:109] neg_lo:[0,0,1] neg_hi:[0,0,1]
	v_pk_mul_f32 v[108:109], v[92:93], v[152:153]
	v_pk_fma_f32 v[150:151], v[98:99], v[176:177], v[138:139]
	v_pk_mul_f32 v[138:139], v[100:101], v[104:105]
	v_mfma_f32_16x16x16_bf16 v[146:149], v[128:129], v[154:155], v[146:149]
	v_fma_f32 v152, v122, v178, v108
	v_fma_f32 v153, v123, v179, v109
	v_pk_mul_f32 v[108:109], v[124:125], v[106:107]
	v_pk_fma_f32 v[176:177], v[90:91], v[168:169], v[138:139] neg_lo:[0,0,1] neg_hi:[0,0,1]
	v_pk_mul_f32 v[138:139], v[96:97], v[106:107]
	v_pk_mul_f32 v[104:105], v[90:91], v[104:105]
	v_mfma_f32_16x16x16_bf16 v[180:183], v[126:127], v[154:155], v[180:183]
	v_fma_f32 v178, v96, v170, -v108
	v_fma_f32 v179, v97, v171, -v109
	v_pk_fma_f32 v[170:171], v[124:125], v[170:171], v[138:139]
	v_pk_fma_f32 v[168:169], v[100:101], v[168:169], v[104:105]
	v_pk_mul_f32 v[104:105], v[118:119], v[174:175]
	v_pk_mul_f32 v[138:139], v[88:89], v[172:173]
	v_mfma_f32_16x16x16_bf16 v[150:153], v[132:133], v[154:155], v[150:153]
	v_mfma_f32_16x16x16_bf16 v[106:109], v[134:135], v[154:155], v[176:179]
	s_nop 2
	v_fma_f32 v178, v80, v142, -v104
	v_fma_f32 v179, v81, v143, -v105
	v_pk_fma_f32 v[176:177], v[78:79], v[140:141], v[138:139] neg_lo:[0,0,1] neg_hi:[0,0,1]
	v_pk_mul_f32 v[104:105], v[80:81], v[174:175]
	v_pk_mul_f32 v[138:139], v[78:79], v[172:173]
	v_mfma_f32_16x16x16_bf16 v[164:167], v[130:131], v[154:155], v[164:167]
	v_fma_f32 v142, v118, v142, v104
	v_fma_f32 v143, v119, v143, v105
	v_pk_fma_f32 v[140:141], v[88:89], v[140:141], v[138:139]
	v_pk_mul_f32 v[104:105], v[120:121], v[148:149]
	v_mfma_f32_16x16x16_bf16 v[168:171], v[136:137], v[154:155], v[168:171]
	v_fma_f32 v186, v86, v182, -v104
	v_fma_f32 v187, v87, v183, -v105
	v_pk_mul_f32 v[104:105], v[86:87], v[148:149]
	v_mfma_f32_16x16x16_bf16 v[138:141], v[116:117], v[156:157], v[140:143]
	v_fma_f32 v148, v120, v182, v104
	v_fma_f32 v149, v121, v183, v105
	v_pk_mul_f32 v[104:105], v[122:123], v[152:153]
	v_pk_mul_f32 v[142:143], v[94:95], v[146:147]
	v_mfma_f32_16x16x16_bf16 v[174:177], v[114:115], v[156:157], v[176:179]
	v_fma_f32 v184, v82, v180, -v142
	v_fma_f32 v185, v83, v181, -v143
	v_pk_mul_f32 v[142:143], v[82:83], v[146:147]
	s_nop 0
	v_pk_fma_f32 v[146:147], v[94:95], v[180:181], v[142:143]
	v_pk_mul_f32 v[142:143], v[98:99], v[150:151]
	v_pk_fma_f32 v[180:181], v[92:93], v[166:167], v[104:105] neg_lo:[0,0,1] neg_hi:[0,0,1]
	v_pk_fma_f32 v[178:179], v[84:85], v[164:165], v[142:143] neg_lo:[0,0,1] neg_hi:[0,0,1]
	v_pk_mul_f32 v[104:105], v[92:93], v[152:153]
	v_pk_mul_f32 v[142:143], v[84:85], v[150:151]
	v_pk_fma_f32 v[166:167], v[122:123], v[166:167], v[104:105]
	v_pk_fma_f32 v[164:165], v[98:99], v[164:165], v[142:143]
	v_pk_mul_f32 v[104:105], v[124:125], v[170:171]
	v_pk_mul_f32 v[142:143], v[100:101], v[168:169]
	v_mfma_f32_16x16x16_bf16 v[152:155], v[130:131], v[156:157], v[178:181]
	s_nop 2
	v_fma_f32 v180, v96, v108, -v104
	v_fma_f32 v181, v97, v109, -v105
	v_pk_fma_f32 v[178:179], v[90:91], v[106:107], v[142:143] neg_lo:[0,0,1] neg_hi:[0,0,1]
	v_pk_mul_f32 v[104:105], v[96:97], v[170:171]
	v_pk_mul_f32 v[142:143], v[90:91], v[168:169]
	v_pk_fma_f32 v[108:109], v[124:125], v[108:109], v[104:105]
	v_pk_fma_f32 v[106:107], v[100:101], v[106:107], v[142:143]
	v_mfma_f32_16x16x16_bf16 v[184:187], v[126:127], v[156:157], v[184:187]
	v_mul_f32_e64 v142, v88, v138
	v_mul_f32_e64 v143, v89, v139
	v_pk_mul_f32 v[138:139], v[78:79], v[138:139]
	v_mfma_f32_16x16x16_bf16 v[146:149], v[128:129], v[156:157], v[146:149]
	v_mfma_f32_16x16x16_bf16 v[164:167], v[132:133], v[156:157], v[164:167]
	v_mfma_f32_16x16x16_bf16 v[170:173], v[134:135], v[156:157], v[178:181]
	v_mfma_f32_16x16x16_bf16 v[104:107], v[136:137], v[156:157], v[106:109]
	ds_read2_b64 v[156:159], v163 offset0:56 offset1:60
	s_nop 0
	v_pk_fma_f32 v[178:179], v[78:79], v[174:175], v[142:143] neg_lo:[0,0,1] neg_hi:[0,0,1]
	v_pk_fma_f32 v[174:175], v[88:89], v[174:175], v[138:139]
	v_pk_mul_f32 v[108:109], v[118:119], v[140:141]
	v_pk_mul_f32 v[138:139], v[94:95], v[146:147]
	v_pk_fma_f32 v[180:181], v[80:81], v[176:177], v[108:109] neg_lo:[0,0,1] neg_hi:[0,0,1]
	v_pk_mul_f32 v[108:109], v[80:81], v[140:141]
	s_nop 0
	v_pk_fma_f32 v[176:177], v[118:119], v[176:177], v[108:109]
	v_pk_mul_f32 v[108:109], v[120:121], v[148:149]
	s_waitcnt lgkmcnt(0)
; #define LAS __attribute__((address_space(3)))
; #define S5_UPDATE(K, hre, him, xq) do { const v2u xb_ = (xq); \
;     _Pragma("unroll") for (int j = 0; j < 4; ++j) { const f32x4 cre_ = K.ar[j] * hre[j] - K.ai[j] * him[j], cim_ = K.ar[j] * him[j] + K.ai[j] * hre[j]; \
;         hre[j] = MFMA16K16(K.Bf[2 * j], xb_, cre_); him[j] = MFMA16K16(K.Bf[2 * j + 1], xb_, cim_); } } while (0)
; __device__ __forceinline__ void s5_prompt_task(const Args& a, const Ctx& C, int b, int g, v4u (&xv)[8]) {
;     ...
;     for (int t = 0; t < 16; ++t) { const v2u xq = *(const LAS v2u*)(xsl + t * 32); S5_UPDATE(K, hre, him, xq); }
; #pragma unroll
;     for (int j = 0; j < 4; ++j) { LAS float* d = SH + chunk * 132 + 2 * (16 * j + 4 * q);
;         *(LAS f32x4*)d = (f32x4){hre[j][0], him[j][0], hre[j][1], him[j][1]}; *(LAS f32x4*)(d + 4) = (f32x4){hre[j][2], him[j][2], hre[j][3], him[j][3]}; }
;     v2u zq[4];
; #pragma unroll
;     for (int t = 0; t < 4; ++t) zq[t] = __builtin_nontemporal_load((const v2u*)(ZBg + (size_t)(16 * chunk + t) * 16 + 4 * q));
;     ...
;     { const float* A16 = (const float*)(a.ws + WS_S5C + S5C_A16) + (size_t)g * 128; const float* A256 = (const float*)(a.ws + WS_S5C + S5C_A256) + (size_t)g * 128;
	v_mfma_f32_16x16x16_bf16 v[140:143], v[114:115], v[156:157], v[178:181]
	s_nop 2
	v_fma_f32 v180, v86, v186, -v108
	v_fma_f32 v181, v87, v187, -v109
	v_pk_fma_f32 v[178:179], v[82:83], v[184:185], v[138:139] neg_lo:[0,0,1] neg_hi:[0,0,1]
	v_pk_mul_f32 v[138:139], v[82:83], v[146:147]
	v_mfma_f32_16x16x16_bf16 v[174:177], v[116:117], v[156:157], v[174:177]
	v_mul_f32_e64 v108, v86, v148
	v_mul_f32_e64 v109, v87, v149
	v_mfma_f32_16x16x16_bf16 v[148:151], v[126:127], v[156:157], v[178:181]
	s_nop 2
	v_fma_f32 v178, v94, v184, v138
	v_fma_f32 v179, v95, v185, v139
	v_pk_mul_f32 v[138:139], v[98:99], v[164:165]
	v_pk_fma_f32 v[180:181], v[120:121], v[186:187], v[108:109]
	v_pk_mul_f32 v[108:109], v[122:123], v[166:167]
	v_pk_fma_f32 v[182:183], v[84:85], v[152:153], v[138:139] neg_lo:[0,0,1] neg_hi:[0,0,1]
	v_pk_mul_f32 v[138:139], v[84:85], v[164:165]
	v_mfma_f32_16x16x16_bf16 v[178:181], v[128:129], v[156:157], v[178:181]
	v_fma_f32 v184, v92, v154, -v108
	v_fma_f32 v185, v93, v155, -v109
	v_pk_mul_f32 v[108:109], v[92:93], v[166:167]
	v_pk_fma_f32 v[152:153], v[98:99], v[152:153], v[138:139]
	v_pk_mul_f32 v[138:139], v[100:101], v[104:105]
	v_mfma_f32_16x16x16_bf16 v[166:169], v[130:131], v[156:157], v[182:185]
	v_fma_f32 v154, v122, v154, v108
	v_fma_f32 v155, v123, v155, v109
	v_pk_mul_f32 v[108:109], v[124:125], v[106:107]
	v_pk_mul_f32 v[104:105], v[90:91], v[104:105]
	v_pk_fma_f32 v[182:183], v[90:91], v[170:171], v[138:139] neg_lo:[0,0,1] neg_hi:[0,0,1]
	v_pk_mul_f32 v[138:139], v[96:97], v[106:107]
	v_mfma_f32_16x16x16_bf16 v[152:155], v[132:133], v[156:157], v[152:155]
	v_fma_f32 v184, v96, v172, -v108
	v_fma_f32 v185, v97, v173, -v109
	v_pk_fma_f32 v[172:173], v[124:125], v[172:173], v[138:139]
	v_pk_mul_f32 v[138:139], v[88:89], v[174:175]
	v_mfma_f32_16x16x16_bf16 v[106:109], v[134:135], v[156:157], v[182:185]
	v_fma_f32 v170, v100, v170, v104
	v_fma_f32 v171, v101, v171, v105
	v_pk_mul_f32 v[104:105], v[118:119], v[176:177]
	v_pk_fma_f32 v[182:183], v[78:79], v[140:141], v[138:139] neg_lo:[0,0,1] neg_hi:[0,0,1]
	v_pk_mul_f32 v[78:79], v[78:79], v[174:175]
	v_mfma_f32_16x16x16_bf16 v[170:173], v[136:137], v[156:157], v[170:173]
	v_fma_f32 v184, v80, v142, -v104
	v_fma_f32 v185, v81, v143, -v105
	v_pk_fma_f32 v[78:79], v[88:89], v[140:141], v[78:79]
	v_pk_mul_f32 v[88:89], v[120:121], v[180:181]
	v_pk_mul_f32 v[104:105], v[94:95], v[178:179]
	v_pk_fma_f32 v[140:141], v[86:87], v[150:151], v[88:89] neg_lo:[0,0,1] neg_hi:[0,0,1]
	v_pk_fma_f32 v[138:139], v[82:83], v[148:149], v[104:105] neg_lo:[0,0,1] neg_hi:[0,0,1]
	v_pk_mul_f32 v[82:83], v[82:83], v[178:179]
	v_pk_mul_f32 v[80:81], v[80:81], v[176:177]
	v_pk_mul_f32 v[104:105], v[86:87], v[180:181]
	v_mfma_f32_16x16x16_bf16 v[86:89], v[126:127], v[158:159], v[138:141]
	v_fma_f32 v80, v118, v142, v80
	v_fma_f32 v81, v119, v143, v81
	s_nop 0
	v_pk_fma_f32 v[138:139], v[94:95], v[148:149], v[82:83]
	v_pk_mul_f32 v[82:83], v[122:123], v[154:155]
	v_pk_fma_f32 v[140:141], v[120:121], v[150:151], v[104:105]
	v_pk_mul_f32 v[94:95], v[98:99], v[152:153]
	v_pk_fma_f32 v[148:149], v[92:93], v[168:169], v[82:83] neg_lo:[0,0,1] neg_hi:[0,0,1]
	v_pk_mul_f32 v[82:83], v[92:93], v[154:155]
	v_pk_mul_f32 v[104:105], v[84:85], v[152:153]
	v_mfma_f32_16x16x16_bf16 v[182:185], v[114:115], v[158:159], v[182:185]
	v_fma_f32 v146, v84, v166, -v94
	v_fma_f32 v147, v85, v167, -v95
	v_pk_fma_f32 v[84:85], v[122:123], v[168:169], v[82:83]
	v_pk_fma_f32 v[82:83], v[98:99], v[166:167], v[104:105]
	v_mfma_f32_16x16x16_bf16 v[78:81], v[116:117], v[158:159], v[78:81]
	v_mul_f32_e64 v104, v100, v170
	v_mul_f32_e64 v105, v101, v171
	v_pk_mul_f32 v[98:99], v[124:125], v[172:173]
	v_mov_b32_e32 v102, v183
	v_mfma_f32_16x16x16_bf16 v[138:141], v[128:129], v[158:159], v[138:141]
	v_lshlrev_b32_e32 v152, 3, v162
	s_nop 1
	v_mov_b32_e32 v103, v79
	v_mov_b32_e32 v79, v80
	v_mfma_f32_16x16x16_bf16 v[92:95], v[130:131], v[158:159], v[146:149]
	v_mov_b32_e32 v80, v185
	v_mov_b32_e32 v153, v111
	s_nop 0
	v_pk_fma_f32 v[146:147], v[90:91], v[106:107], v[104:105] neg_lo:[0,0,1] neg_hi:[0,0,1]
	v_pk_mul_f32 v[104:105], v[96:97], v[172:173]
	v_pk_mul_f32 v[90:91], v[90:91], v[170:171]
	v_mfma_f32_16x16x16_bf16 v[82:85], v[132:133], v[158:159], v[82:85]
	v_fma_f32 v148, v96, v108, -v98
	v_fma_f32 v149, v97, v109, -v99
	v_pk_fma_f32 v[108:109], v[124:125], v[108:109], v[104:105]
	v_pk_fma_f32 v[106:107], v[100:101], v[106:107], v[90:91]
	v_mfma_f32_16x16x16_bf16 v[96:99], v[134:135], v[158:159], v[146:149]
	v_mov_b32_e32 v101, v78
	v_mov_b32_e32 v78, v184
	ds_write_b128 v3, v[78:81] offset:16
	v_mfma_f32_16x16x16_bf16 v[104:107], v[136:137], v[158:159], v[106:109]
	v_mov_b32_e32 v78, v86
	v_mov_b32_e32 v79, v138
	v_mov_b32_e32 v80, v87
	v_mov_b32_e32 v81, v139
	ds_write_b128 v3, v[78:81] offset:128
	v_mov_b32_e32 v78, v92
	v_mov_b32_e32 v79, v82
	v_mov_b32_e32 v80, v93
	v_mov_b32_e32 v81, v83
	ds_write_b128 v3, v[78:81] offset:256
	v_mov_b32_e32 v78, v96
	v_mov_b32_e32 v79, v104
	v_mov_b32_e32 v80, v97
	v_mov_b32_e32 v81, v105
	v_mov_b32_e32 v138, v88
	v_mov_b32_e32 v139, v140
	v_mov_b32_e32 v140, v89
	v_mov_b32_e32 v82, v94
	v_mov_b32_e32 v83, v84
	v_mov_b32_e32 v84, v95
	ds_write_b128 v3, v[78:81] offset:384
	v_lshl_add_u64 v[78:79], s[4:5], 0, v[110:111]
	s_mov_b64 s[4:5], 0xd400000
	v_mov_b32_e32 v110, v7
	v_mov_b32_e32 v100, v182
	ds_write_b128 v3, v[138:141] offset:144
	ds_write_b128 v3, v[82:85] offset:272
	v_mov_b32_e32 v104, v98
	v_mov_b32_e32 v105, v106
	v_mov_b32_e32 v106, v99
	v_lshl_add_u64 v[138:139], v[78:79], 0, s[4:5]
	v_lshlrev_b64 v[78:79], 5, v[110:111]
	v_or_b32_e32 v80, 1, v7
	v_mov_b32_e32 v81, v111
	v_or_b32_e32 v82, 2, v7
	v_mov_b32_e32 v83, v111
	v_or_b32_e32 v84, 3, v7
	v_mov_b32_e32 v85, v111
	ds_write_b128 v3, v[100:103]
	ds_write_b128 v3, v[104:107] offset:400
	v_lshl_add_u64 v[78:79], v[138:139], 0, v[78:79]
	v_lshlrev_b64 v[80:81], 5, v[80:81]
	v_lshlrev_b64 v[82:83], 5, v[82:83]
	v_lshlrev_b64 v[84:85], 5, v[84:85]
	v_lshl_add_u64 v[80:81], v[138:139], 0, v[80:81]
	v_lshl_add_u64 v[82:83], v[138:139], 0, v[82:83]
	v_lshl_add_u64 v[84:85], v[138:139], 0, v[84:85]
	global_load_dwordx2 v[226:227], v[78:79], off nt
	global_load_dwordx2 v[228:229], v[80:81], off nt
	global_load_dwordx2 v[230:231], v[82:83], off nt
	global_load_dwordx2 v[232:233], v[84:85], off nt
	v_lshl_add_u64 v[78:79], s[6:7], 0, v[152:153]
	v_add_co_u32_e32 v80, vcc, s2, v78
	s_waitcnt lgkmcnt(0)
; #define LAS __attribute__((address_space(3)))
; __device__ __forceinline__ void s5_prompt_task(const Args& a, const Ctx& C, int b, int g, v4u (&xv)[8]) {
;     ...
;     { const float* A16 = (const float*)(a.ws + WS_S5C + S5C_A16) + (size_t)g * 128; const float* A256 = (const float*)(a.ws + WS_S5C + S5C_A256) + (size_t)g * 128;
;       const float a16r = A16[2 * lane], a16i = A16[2 * lane + 1], a256r = A256[2 * lane], a256i = A256[2 * lane + 1];
;       v2f sv[16];
; #pragma unroll
;       for (int i = 0; i < 16; ++i) sv[i] = *(const LAS v2f*)(SH + (16 * w + i) * 132 + 2 * lane);
;       float tr = 0.f, ti = 0.f;
; #pragma unroll
;       for (int i = 0; i < 16; ++i) { const float nr = a16r * tr - a16i * ti + sv[i][0], ni = a16r * ti + a16i * tr + sv[i][1]; tr = nr; ti = ni; }
;       TW[w * 128 + 2 * lane] = tr; TW[w * 128 + 2 * lane + 1] = ti;
;       __syncthreads();
	s_mov_b32 s2, 0x2310000
	s_nop 0
	v_addc_co_u32_e32 v81, vcc, 0, v79, vcc
	v_add_co_u32_e32 v78, vcc, s2, v78
	v_add_u32_e32 v7, s8, v152
	s_nop 0
	v_addc_co_u32_e32 v79, vcc, 0, v79, vcc
	s_mul_i32 s4, s82, 0x2100
	v_add_u32_e32 v7, s4, v7
	v_add_u32_e32 v11, 0x800, v7
	ds_read2_b64 v[106:109], v7 offset1:66
	ds_read2_b64 v[102:105], v7 offset0:132 offset1:198
	ds_read2_b64 v[98:101], v11 offset0:8 offset1:74
	ds_read2_b64 v[94:97], v11 offset0:140 offset1:206
	v_add_u32_e32 v11, 0x1000, v7
	ds_read2_b64 v[90:93], v11 offset0:16 offset1:82
	ds_read2_b64 v[86:89], v11 offset0:148 offset1:214
	v_add_u32_e32 v11, 0x1800, v7
	ds_read2_b64 v[82:85], v11 offset0:24 offset1:90
	ds_read2_b64 v[78:81], v11 offset0:156 offset1:222
	s_lshl_b32 s4, s82, 9
	s_add_i32 s4, s4, 0
	s_mov_b32 s2, 0
	s_cmp_lt_u32 s84, 64
	s_waitcnt vmcnt(4)
	v_mov_b32_e32 v148, v234
	v_mov_b32_e32 v149, v235
	v_mov_b32_e32 v150, v236
	v_mov_b32_e32 v151, v237
	v_mul_f32_e32 v11, 0, v148
	v_mul_f32_e32 v155, 0, v149
	v_sub_f32_e32 v154, v11, v155
	v_fmac_f32_e32 v155, 0, v148
	s_waitcnt lgkmcnt(7)
	v_pk_add_f32 v[154:155], v[154:155], v[106:107]
	v_add_u32_e32 v11, s4, v152
	v_pk_mul_f32 v[156:157], v[148:149], v[154:155] op_sel:[1,1] op_sel_hi:[0,1]
	v_pk_fma_f32 v[158:159], v[148:149], v[154:155], v[156:157] op_sel_hi:[1,0,1]
	v_pk_fma_f32 v[156:157], v[148:149], v[154:155], v[156:157] op_sel_hi:[1,0,1] neg_lo:[0,0,1] neg_hi:[0,0,1]
	v_add_u32_e32 v11, 0x21000, v11
	v_mov_b32_e32 v157, v159
	v_pk_add_f32 v[156:157], v[108:109], v[156:157]
	v_mov_b32_e32 v152, v111
	v_pk_mul_f32 v[158:159], v[148:149], v[156:157] op_sel:[1,1] op_sel_hi:[0,1]
	v_pk_fma_f32 v[164:165], v[148:149], v[156:157], v[158:159] op_sel_hi:[1,0,1]
	v_pk_fma_f32 v[158:159], v[148:149], v[156:157], v[158:159] op_sel_hi:[1,0,1] neg_lo:[0,0,1] neg_hi:[0,0,1]
	s_nop 0
	v_mov_b32_e32 v159, v165
	s_waitcnt lgkmcnt(6)
	v_pk_add_f32 v[158:159], v[102:103], v[158:159]
	s_nop 0
	v_pk_mul_f32 v[164:165], v[148:149], v[158:159] op_sel:[1,1] op_sel_hi:[0,1]
	v_pk_fma_f32 v[166:167], v[148:149], v[158:159], v[164:165] op_sel_hi:[1,0,1]
	v_pk_fma_f32 v[164:165], v[148:149], v[158:159], v[164:165] op_sel_hi:[1,0,1] neg_lo:[0,0,1] neg_hi:[0,0,1]
	s_nop 0
	v_mov_b32_e32 v165, v167
	v_pk_add_f32 v[164:165], v[104:105], v[164:165]
	s_nop 0
	v_pk_mul_f32 v[166:167], v[148:149], v[164:165] op_sel:[1,1] op_sel_hi:[0,1]
	v_pk_fma_f32 v[168:169], v[148:149], v[164:165], v[166:167] op_sel_hi:[1,0,1]
	v_pk_fma_f32 v[166:167], v[148:149], v[164:165], v[166:167] op_sel_hi:[1,0,1] neg_lo:[0,0,1] neg_hi:[0,0,1]
	s_nop 0
	v_mov_b32_e32 v167, v169
	s_waitcnt lgkmcnt(5)
	v_pk_add_f32 v[166:167], v[98:99], v[166:167]
	s_nop 0
	v_pk_mul_f32 v[168:169], v[148:149], v[166:167] op_sel:[1,1] op_sel_hi:[0,1]
	v_pk_fma_f32 v[170:171], v[148:149], v[166:167], v[168:169] op_sel_hi:[1,0,1]
	v_pk_fma_f32 v[168:169], v[148:149], v[166:167], v[168:169] op_sel_hi:[1,0,1] neg_lo:[0,0,1] neg_hi:[0,0,1]
	s_nop 0
	v_mov_b32_e32 v169, v171
	v_pk_add_f32 v[168:169], v[100:101], v[168:169]
	s_nop 0
	v_pk_mul_f32 v[170:171], v[148:149], v[168:169] op_sel:[1,1] op_sel_hi:[0,1]
	v_pk_fma_f32 v[172:173], v[148:149], v[168:169], v[170:171] op_sel_hi:[1,0,1]
	v_pk_fma_f32 v[170:171], v[148:149], v[168:169], v[170:171] op_sel_hi:[1,0,1] neg_lo:[0,0,1] neg_hi:[0,0,1]
	s_nop 0
	v_mov_b32_e32 v171, v173
	s_waitcnt lgkmcnt(4)
	v_pk_add_f32 v[170:171], v[94:95], v[170:171]
	s_nop 0
	v_pk_mul_f32 v[172:173], v[148:149], v[170:171] op_sel:[1,1] op_sel_hi:[0,1]
	v_pk_fma_f32 v[174:175], v[148:149], v[170:171], v[172:173] op_sel_hi:[1,0,1]
	v_pk_fma_f32 v[172:173], v[148:149], v[170:171], v[172:173] op_sel_hi:[1,0,1] neg_lo:[0,0,1] neg_hi:[0,0,1]
	s_nop 0
	v_mov_b32_e32 v173, v175
	v_pk_add_f32 v[172:173], v[96:97], v[172:173]
	s_nop 0
	v_pk_mul_f32 v[174:175], v[148:149], v[172:173] op_sel:[1,1] op_sel_hi:[0,1]
	v_pk_fma_f32 v[176:177], v[148:149], v[172:173], v[174:175] op_sel_hi:[1,0,1]
	v_pk_fma_f32 v[174:175], v[148:149], v[172:173], v[174:175] op_sel_hi:[1,0,1] neg_lo:[0,0,1] neg_hi:[0,0,1]
	s_nop 0
	v_mov_b32_e32 v175, v177
	s_waitcnt lgkmcnt(3)
	v_pk_add_f32 v[174:175], v[90:91], v[174:175]
	s_nop 0
	v_pk_mul_f32 v[176:177], v[148:149], v[174:175] op_sel:[1,1] op_sel_hi:[0,1]
	v_pk_fma_f32 v[178:179], v[148:149], v[174:175], v[176:177] op_sel_hi:[1,0,1]
	v_pk_fma_f32 v[176:177], v[148:149], v[174:175], v[176:177] op_sel_hi:[1,0,1] neg_lo:[0,0,1] neg_hi:[0,0,1]
	s_nop 0
	v_mov_b32_e32 v177, v179
	v_pk_add_f32 v[176:177], v[92:93], v[176:177]
	s_nop 0
	v_pk_mul_f32 v[178:179], v[148:149], v[176:177] op_sel:[1,1] op_sel_hi:[0,1]
	v_pk_fma_f32 v[180:181], v[148:149], v[176:177], v[178:179] op_sel_hi:[1,0,1]
	v_pk_fma_f32 v[178:179], v[148:149], v[176:177], v[178:179] op_sel_hi:[1,0,1] neg_lo:[0,0,1] neg_hi:[0,0,1]
	s_nop 0
	v_mov_b32_e32 v179, v181
	s_waitcnt lgkmcnt(2)
	v_pk_add_f32 v[178:179], v[86:87], v[178:179]
	s_nop 0
	v_pk_mul_f32 v[180:181], v[148:149], v[178:179] op_sel:[1,1] op_sel_hi:[0,1]
	v_pk_fma_f32 v[182:183], v[148:149], v[178:179], v[180:181] op_sel_hi:[1,0,1]
	v_pk_fma_f32 v[180:181], v[148:149], v[178:179], v[180:181] op_sel_hi:[1,0,1] neg_lo:[0,0,1] neg_hi:[0,0,1]
	s_nop 0
	v_mov_b32_e32 v181, v183
	v_pk_add_f32 v[182:183], v[88:89], v[180:181]
	s_nop 0
	v_pk_mul_f32 v[180:181], v[148:149], v[182:183] op_sel:[1,1] op_sel_hi:[0,1]
	v_pk_fma_f32 v[184:185], v[148:149], v[182:183], v[180:181] op_sel_hi:[1,0,1]
	v_pk_fma_f32 v[180:181], v[148:149], v[182:183], v[180:181] op_sel_hi:[1,0,1] neg_lo:[0,0,1] neg_hi:[0,0,1]
	s_nop 0
	v_mov_b32_e32 v181, v185
	s_waitcnt lgkmcnt(1)
	v_pk_add_f32 v[184:185], v[82:83], v[180:181]
	s_nop 0
	v_pk_mul_f32 v[180:181], v[148:149], v[184:185] op_sel:[1,1] op_sel_hi:[0,1]
	v_pk_fma_f32 v[186:187], v[148:149], v[184:185], v[180:181] op_sel_hi:[1,0,1]
	v_pk_fma_f32 v[180:181], v[148:149], v[184:185], v[180:181] op_sel_hi:[1,0,1] neg_lo:[0,0,1] neg_hi:[0,0,1]
	s_nop 0
	v_mov_b32_e32 v181, v187
	v_pk_add_f32 v[186:187], v[84:85], v[180:181]
	s_nop 0
	v_pk_mul_f32 v[180:181], v[148:149], v[186:187] op_sel:[1,1] op_sel_hi:[0,1]
	v_pk_fma_f32 v[188:189], v[148:149], v[186:187], v[180:181] op_sel_hi:[1,0,1]
	v_pk_fma_f32 v[180:181], v[148:149], v[186:187], v[180:181] op_sel_hi:[1,0,1] neg_lo:[0,0,1] neg_hi:[0,0,1]
	s_nop 0
	v_mov_b32_e32 v181, v189
	s_waitcnt lgkmcnt(0)
	v_pk_add_f32 v[188:189], v[78:79], v[180:181]
	s_nop 0
	v_pk_mul_f32 v[180:181], v[148:149], v[188:189] op_sel:[1,1] op_sel_hi:[0,1]
	v_pk_fma_f32 v[198:199], v[148:149], v[188:189], v[180:181] op_sel_hi:[1,0,1]
	v_pk_fma_f32 v[180:181], v[148:149], v[188:189], v[180:181] op_sel_hi:[1,0,1] neg_lo:[0,0,1] neg_hi:[0,0,1]
	s_nop 0
	v_mov_b32_e32 v181, v199
	v_pk_add_f32 v[180:181], v[80:81], v[180:181]
	ds_write_b64 v11, v[180:181]
	s_waitcnt lgkmcnt(0)
	s_barrier
; __device__ __forceinline__ void s5_prompt_task(const Args& a, const Ctx& C, int b, int g, v4u (&xv)[8]) {
;     ...
;       float hr = 0.f, hi = 0.f;
;       for (int v = 0; v < w; ++v) { const float sr = TW[v * 128 + 2 * lane], si = TW[v * 128 + 2 * lane + 1];
;           const float nr = a256r * hr - a256i * hi + sr, ni = a256r * hi + a256i * hr + si; hr = nr; hi = ni; }
	s_cbranch_scc1 .LBB0_985
	s_add_i32 s4, s82, -1
	s_cmp_lt_u32 s4, 7
	v_mov_b32_e32 v160, v111
	v_mov_b32_e32 v152, v111
	s_cbranch_scc1 .LBB0_977
	v_lshl_add_u32 v11, v162, 3, 0
	s_and_b32 s2, s82, 0x3fffff8
	s_waitcnt vmcnt(4)
	v_pk_mov_b32 v[154:155], v[150:151], v[150:151] op_sel:[1,0]
	s_mov_b32 s4, 0
	v_add_u32_e32 v11, 0x21000, v11
	v_mov_b32_e32 v152, 0
	v_mov_b32_e32 v160, 0

; __device__ __forceinline__ void s5_prompt_task(const Args& a, const Ctx& C, int b, int g, v4u (&xv)[8]) {
;     ...
;       float hr = 0.f, hi = 0.f;
;       for (int v = 0; v < w; ++v) { const float sr = TW[v * 128 + 2 * lane], si = TW[v * 128 + 2 * lane + 1];
;           const float nr = a256r * hr - a256i * hi + sr, ni = a256r * hi + a256i * hr + si; hr = nr; hi = ni; }
.LBB0_977:
	s_bfe_u32 s4, s84, 0x30006
	v_pk_mov_b32 v[180:181], v[148:149], v[148:149] op_sel:[1,0]
	s_cmp_eq_u32 s4, 0
	s_cbranch_scc1 .LBB0_983
	s_lshl_b32 s2, s2, 9
	s_add_i32 s2, s2, 0
	v_lshl_add_u32 v11, v162, 3, s2
	s_waitcnt vmcnt(4)
	v_pk_mov_b32 v[154:155], v[150:151], v[150:151] op_sel:[1,0]
	v_add_u32_e32 v11, 0x21000, v11
	v_mov_b32_e32 v153, v160

; #define LAS __attribute__((address_space(3)))
; __device__ __forceinline__ void s5_prompt_task(const Args& a, const Ctx& C, int b, int g, v4u (&xv)[8]) {
;     ...
; #pragma unroll
;       for (int i = 0; i < 16; ++i) { *(LAS v2f*)(SH + (16 * w + i) * 132 + 2 * lane) = (v2f){hr, hi};
;           const float nr = a16r * hr - a16i * hi + sv[i][0], ni = a16r * hi + a16i * hr + sv[i][1]; hr = nr; hi = ni; }
.LBB0_984:
	s_waitcnt vmcnt(4)
	v_pk_mul_f32 v[150:151], v[180:181], v[152:153] op_sel:[0,1]
	s_nop 0
	v_pk_fma_f32 v[154:155], v[148:149], v[152:153], v[150:151] op_sel_hi:[1,0,1]
	v_pk_fma_f32 v[150:151], v[148:149], v[152:153], v[150:151] op_sel_hi:[1,0,1] neg_lo:[0,0,1] neg_hi:[0,0,1]
	s_nop 0
	v_mov_b32_e32 v151, v155
	v_pk_add_f32 v[154:155], v[106:107], v[150:151]
	s_nop 0
	v_pk_mul_f32 v[106:107], v[180:181], v[154:155] op_sel:[0,1]
	s_nop 0
	v_pk_fma_f32 v[150:151], v[148:149], v[154:155], v[106:107] op_sel_hi:[1,0,1]
	v_pk_fma_f32 v[106:107], v[148:149], v[154:155], v[106:107] op_sel_hi:[1,0,1] neg_lo:[0,0,1] neg_hi:[0,0,1]
	s_nop 0
	v_mov_b32_e32 v107, v151
	v_pk_add_f32 v[156:157], v[108:109], v[106:107]
	s_nop 0
	v_pk_mul_f32 v[106:107], v[180:181], v[156:157] op_sel:[0,1]
	s_nop 0
	v_pk_fma_f32 v[108:109], v[148:149], v[156:157], v[106:107] op_sel_hi:[1,0,1]
	v_pk_fma_f32 v[106:107], v[148:149], v[156:157], v[106:107] op_sel_hi:[1,0,1] neg_lo:[0,0,1] neg_hi:[0,0,1]
	s_nop 0
	v_mov_b32_e32 v107, v109
	v_pk_add_f32 v[158:159], v[102:103], v[106:107]
	s_nop 0
	v_pk_mul_f32 v[102:103], v[180:181], v[158:159] op_sel:[0,1]
	s_nop 0
	v_pk_fma_f32 v[106:107], v[148:149], v[158:159], v[102:103] op_sel_hi:[1,0,1]
	v_pk_fma_f32 v[102:103], v[148:149], v[158:159], v[102:103] op_sel_hi:[1,0,1] neg_lo:[0,0,1] neg_hi:[0,0,1]
	s_nop 0
	v_mov_b32_e32 v103, v107
	v_pk_add_f32 v[164:165], v[104:105], v[102:103]
	s_nop 0
	v_pk_mul_f32 v[102:103], v[180:181], v[164:165] op_sel:[0,1]
	s_nop 0
	v_pk_fma_f32 v[104:105], v[148:149], v[164:165], v[102:103] op_sel_hi:[1,0,1]
	v_pk_fma_f32 v[102:103], v[148:149], v[164:165], v[102:103] op_sel_hi:[1,0,1] neg_lo:[0,0,1] neg_hi:[0,0,1]
	s_nop 0
	v_mov_b32_e32 v103, v105
	v_pk_add_f32 v[166:167], v[98:99], v[102:103]
	s_nop 0
	v_pk_mul_f32 v[98:99], v[180:181], v[166:167] op_sel:[0,1]
	s_nop 0
	v_pk_fma_f32 v[102:103], v[148:149], v[166:167], v[98:99] op_sel_hi:[1,0,1]
	v_pk_fma_f32 v[98:99], v[148:149], v[166:167], v[98:99] op_sel_hi:[1,0,1] neg_lo:[0,0,1] neg_hi:[0,0,1]
	s_nop 0
	v_mov_b32_e32 v99, v103
	v_pk_add_f32 v[168:169], v[100:101], v[98:99]
	s_nop 0
	v_pk_mul_f32 v[98:99], v[180:181], v[168:169] op_sel:[0,1]
	s_nop 0
	v_pk_fma_f32 v[100:101], v[148:149], v[168:169], v[98:99] op_sel_hi:[1,0,1]
	v_pk_fma_f32 v[98:99], v[148:149], v[168:169], v[98:99] op_sel_hi:[1,0,1] neg_lo:[0,0,1] neg_hi:[0,0,1]
	s_nop 0
	v_mov_b32_e32 v99, v101
	v_pk_add_f32 v[170:171], v[94:95], v[98:99]
	s_nop 0
	v_pk_mul_f32 v[94:95], v[180:181], v[170:171] op_sel:[0,1]
	s_nop 0
	v_pk_fma_f32 v[98:99], v[148:149], v[170:171], v[94:95] op_sel_hi:[1,0,1]
	v_pk_fma_f32 v[94:95], v[148:149], v[170:171], v[94:95] op_sel_hi:[1,0,1] neg_lo:[0,0,1] neg_hi:[0,0,1]
	s_nop 0
	v_mov_b32_e32 v95, v99
	v_pk_add_f32 v[172:173], v[96:97], v[94:95]
	s_nop 0
	v_pk_mul_f32 v[94:95], v[180:181], v[172:173] op_sel:[0,1]
	s_nop 0
	v_pk_fma_f32 v[96:97], v[148:149], v[172:173], v[94:95] op_sel_hi:[1,0,1]
	v_pk_fma_f32 v[94:95], v[148:149], v[172:173], v[94:95] op_sel_hi:[1,0,1] neg_lo:[0,0,1] neg_hi:[0,0,1]
	s_nop 0
	v_mov_b32_e32 v95, v97
	v_pk_add_f32 v[174:175], v[90:91], v[94:95]
	s_nop 0
	v_pk_mul_f32 v[90:91], v[180:181], v[174:175] op_sel:[0,1]
	s_nop 0
	v_pk_fma_f32 v[94:95], v[148:149], v[174:175], v[90:91] op_sel_hi:[1,0,1]
	v_pk_fma_f32 v[90:91], v[148:149], v[174:175], v[90:91] op_sel_hi:[1,0,1] neg_lo:[0,0,1] neg_hi:[0,0,1]
	s_nop 0
	v_mov_b32_e32 v91, v95
	v_pk_add_f32 v[176:177], v[92:93], v[90:91]
	s_nop 0
	v_pk_mul_f32 v[90:91], v[180:181], v[176:177] op_sel:[0,1]
	s_nop 0
	v_pk_fma_f32 v[92:93], v[148:149], v[176:177], v[90:91] op_sel_hi:[1,0,1]
	v_pk_fma_f32 v[90:91], v[148:149], v[176:177], v[90:91] op_sel_hi:[1,0,1] neg_lo:[0,0,1] neg_hi:[0,0,1]
	s_nop 0
	v_mov_b32_e32 v91, v93
	v_pk_add_f32 v[178:179], v[86:87], v[90:91]
	s_nop 0
	v_pk_mul_f32 v[86:87], v[180:181], v[178:179] op_sel:[0,1]
	s_nop 0
	v_pk_fma_f32 v[90:91], v[148:149], v[178:179], v[86:87] op_sel_hi:[1,0,1]
	v_pk_fma_f32 v[86:87], v[148:149], v[178:179], v[86:87] op_sel_hi:[1,0,1] neg_lo:[0,0,1] neg_hi:[0,0,1]
	s_nop 0
	v_mov_b32_e32 v87, v91
	v_pk_add_f32 v[182:183], v[88:89], v[86:87]
	s_nop 0
	v_pk_mul_f32 v[86:87], v[180:181], v[182:183] op_sel:[0,1]
	s_nop 0
	v_pk_fma_f32 v[88:89], v[148:149], v[182:183], v[86:87] op_sel_hi:[1,0,1]
	v_pk_fma_f32 v[86:87], v[148:149], v[182:183], v[86:87] op_sel_hi:[1,0,1] neg_lo:[0,0,1] neg_hi:[0,0,1]
	s_nop 0
	v_mov_b32_e32 v87, v89
	v_pk_add_f32 v[184:185], v[82:83], v[86:87]
	s_nop 0
	v_pk_mul_f32 v[82:83], v[180:181], v[184:185] op_sel:[0,1]
	s_nop 0
	v_pk_fma_f32 v[86:87], v[148:149], v[184:185], v[82:83] op_sel_hi:[1,0,1]
	v_pk_fma_f32 v[82:83], v[148:149], v[184:185], v[82:83] op_sel_hi:[1,0,1] neg_lo:[0,0,1] neg_hi:[0,0,1]
	s_nop 0
	v_mov_b32_e32 v83, v87
	v_pk_add_f32 v[186:187], v[84:85], v[82:83]
	s_nop 0
	v_pk_mul_f32 v[82:83], v[180:181], v[186:187] op_sel:[0,1]
	s_nop 0
	v_pk_fma_f32 v[84:85], v[148:149], v[186:187], v[82:83] op_sel_hi:[1,0,1]
	v_pk_fma_f32 v[82:83], v[148:149], v[186:187], v[82:83] op_sel_hi:[1,0,1] neg_lo:[0,0,1] neg_hi:[0,0,1]
	s_nop 0
	v_mov_b32_e32 v83, v85
	v_pk_add_f32 v[188:189], v[78:79], v[82:83]
	s_nop 0
	v_pk_mul_f32 v[78:79], v[180:181], v[188:189] op_sel:[0,1]
	s_nop 0
	v_pk_fma_f32 v[82:83], v[148:149], v[188:189], v[78:79] op_sel_hi:[1,0,1]
	v_pk_fma_f32 v[78:79], v[148:149], v[188:189], v[78:79] op_sel_hi:[1,0,1] neg_lo:[0,0,1] neg_hi:[0,0,1]
	s_nop 0
	v_mov_b32_e32 v79, v83
	v_pk_add_f32 v[180:181], v[80:81], v[78:79]

; #define LAS __attribute__((address_space(3)))
; __device__ __forceinline__ unsigned pk2(float lo, float hi) { return pg8::cvt_pk_bf16(lo, hi); }
; __device__ __forceinline__ bf16x8 pack8(f32x4 lo, f32x4 hi) { v4u w; w.x = pk2(lo[0], lo[1]); w.y = pk2(lo[2], lo[3]); w.z = pk2(hi[0], hi[1]); w.w = pk2(hi[2], hi[3]); return __builtin_bit_cast(bf16x8, w); }
; __device__ __forceinline__ void s5_load_consts(S5C& K, const Args& a, int g, int lane) {
;     ...
;     const float* cre = a.in[I_CRE] + ((size_t)g * 16 + fr) * 64; const float* cim = a.in[I_CIM] + ((size_t)g * 16 + fr) * 64;
; #pragma unroll
;     for (int j = 0; j < 4; ++j) { const f32x4 r4 = *(const f32x4*)(cre + 16 * j + 4 * q), i4 = *(const f32x4*)(cim + 16 * j + 4 * q); K.Cf[j] = pack8(r4, -i4); }
;     const float* wg = a.in[I_WGLU] + (size_t)g * 512;
;     { f32x4 v, gt;
; #pragma unroll
;       for (int e = 0; e < 4; ++e) { v[e] = wg[(4 * q + e) * 32 + fr]; gt[e] = wg[(4 * q + e) * 32 + 16 + fr]; }
;       K.Wv = (v2u){pk2(v[0], v[1]), pk2(v[2], v[3])}; K.Wg = (v2u){pk2(gt[0], gt[1]), pk2(gt[2], gt[3])}; }
; __device__ __forceinline__ void s5_prompt_task(const Args& a, const Ctx& C, int b, int g, v4u (&xv)[8]) {
;     ...
;     for (int j = 0; j < 4; ++j) { const LAS float* s = SH + chunk * 132 + 2 * (16 * j + 4 * q); const f32x4 x0 = *(const LAS f32x4*)s, x1 = *(const LAS f32x4*)(s + 4);
;         hre[j] = (f32x4){x0[0], x0[2], x1[0], x1[2]}; him[j] = (f32x4){x0[1], x0[3], x1[1], x1[3]}; }
.LBB0_987:
	v_xor_b32_e32 v15, 0x80000000, v63
	v_xor_b32_e32 v32, 0x80000000, v62
	v_xor_b32_e32 v7, 0x80000000, v65
	v_xor_b32_e32 v11, 0x80000000, v64
	v_cvt_pk_bf16_f32 v32, v32, v15
	v_xor_b32_e32 v15, 0x80000000, v55
	v_xor_b32_e32 v54, 0x80000000, v54
	v_cvt_pk_bf16_f32 v33, v11, v7
	v_xor_b32_e32 v7, 0x80000000, v57
	v_xor_b32_e32 v11, 0x80000000, v56
	v_cvt_pk_bf16_f32 v50, v50, v51
	v_cvt_pk_bf16_f32 v51, v52, v53
	v_cvt_pk_bf16_f32 v52, v54, v15
	v_xor_b32_e32 v15, 0x80000000, v47
	v_xor_b32_e32 v46, 0x80000000, v46
	v_cvt_pk_bf16_f32 v53, v11, v7
	v_xor_b32_e32 v7, 0x80000000, v49
	v_xor_b32_e32 v11, 0x80000000, v48
	v_cvt_pk_bf16_f32 v42, v42, v43
	v_cvt_pk_bf16_f32 v43, v44, v45
	v_cvt_pk_bf16_f32 v44, v46, v15
	v_xor_b32_e32 v15, 0x80000000, v39
	v_xor_b32_e32 v38, 0x80000000, v38
	s_waitcnt lgkmcnt(0)
	v_cvt_pk_bf16_f32 v30, v58, v59
	v_cvt_pk_bf16_f32 v31, v60, v61
	v_cvt_pk_bf16_f32 v45, v11, v7
	v_xor_b32_e32 v7, 0x80000000, v41
	v_xor_b32_e32 v11, 0x80000000, v40
	v_cvt_pk_bf16_f32 v34, v34, v35
	v_cvt_pk_bf16_f32 v35, v36, v37
	v_cvt_pk_bf16_f32 v36, v38, v15
	ds_read_b128 v[46:49], v3
	ds_read_b128 v[78:81], v3 offset:16
	ds_read_b128 v[54:57], v3 offset:128
	ds_read_b128 v[82:85], v3 offset:144
	ds_read_b128 v[38:41], v3 offset:256
	s_waitcnt vmcnt(4)
	ds_read_b128 v[148:151], v3 offset:272
	ds_read_b128 v[58:61], v3 offset:384
	ds_read_b128 v[152:155], v3 offset:400
	s_lshl_b64 s[4:5], s[70:71], 22
	v_lshlrev_b64 v[62:63], 11, v[110:111]
	v_lshl_add_u64 v[62:63], s[4:5], 0, v[62:63]
	v_or_b32_e32 v62, s1, v62
	v_lshl_add_u64 v[62:63], v[62:63], 0, v[112:113]
	v_lshl_add_u64 v[62:63], s[94:95], 0, v[62:63]
	s_mov_b64 s[0:1], 0x9801c00
	v_cvt_pk_bf16_f32 v37, v11, v7
	v_cvt_pk_bf16_f32 v102, v191, v193
	v_cvt_pk_bf16_f32 v103, v195, v196
	v_cvt_pk_bf16_f32 v104, v161, v190
	v_cvt_pk_bf16_f32 v105, v192, v194
	v_lshl_add_u64 v[106:107], v[62:63], 0, s[0:1]
	s_mov_b32 s0, 0
	s_mov_b32 s1, 0xc3e00000
	v_mov_b32_e32 v109, 0
	s_movk_i32 s2, 0xf000
	s_mov_b64 s[4:5], 0x2000
	v_mov_b32_e32 v111, 0x43e00000
	s_waitcnt lgkmcnt(7)
	v_mov_b32_e32 v62, v47
	v_mov_b32_e32 v63, v49
	s_waitcnt lgkmcnt(6)
	v_mov_b32_e32 v64, v79
	v_mov_b32_e32 v65, v81
	s_waitcnt lgkmcnt(5)
	v_mov_b32_e32 v66, v55
	v_mov_b32_e32 v67, v57
	s_waitcnt lgkmcnt(4)
	v_mov_b32_e32 v68, v83
	v_mov_b32_e32 v69, v85
	s_waitcnt lgkmcnt(3)
	v_mov_b32_e32 v70, v39
	v_mov_b32_e32 v71, v41
	s_waitcnt lgkmcnt(2)
	v_mov_b32_e32 v72, v149
	v_mov_b32_e32 v73, v151
	s_waitcnt lgkmcnt(1)
	v_mov_b32_e32 v74, v59
	v_mov_b32_e32 v75, v61
	s_waitcnt lgkmcnt(0)
	v_mov_b32_e32 v76, v153
	v_mov_b32_e32 v77, v155
	v_mov_b32_e32 v47, v48
	v_mov_b32_e32 v48, v78
	v_mov_b32_e32 v49, v80
	v_mov_b32_e32 v55, v56
	v_mov_b32_e32 v56, v82
	v_mov_b32_e32 v57, v84
	v_mov_b32_e32 v39, v40
	v_mov_b32_e32 v40, v148
	v_mov_b32_e32 v41, v150
	v_mov_b32_e32 v59, v60
	v_mov_b32_e32 v60, v152
	v_mov_b32_e32 v61, v154
